# v6 + SGU units visited in descending order (most recently written rows first)
# speedup vs baseline: 1.0095x; 1.0049x over previous
.LBB0_379:
	s_or_b64 exec, exec, s[36:37]
	v_readlane_b32 s24, v251, 2
	v_readlane_b32 s26, v251, 4
	v_readlane_b32 s27, v251, 5
	s_add_u32 s42, s26, 0x23c00000
	s_addc_u32 s43, s27, 0
	s_add_u32 s44, s26, 0x1b800000
	s_addc_u32 s45, s27, 0
	s_add_u32 s70, s26, 0xc00000
	s_addc_u32 s71, s27, 0
	s_cmpk_lt_i32 s84, 0x840
	s_cselect_b64 s[72:73], -1, 0
	s_ashr_i32 s47, s84, 31
	s_lshr_b32 s0, s47, 29
	s_add_i32 s0, s84, s0
	s_ashr_i32 s31, s0, 3
	s_and_b32 s0, s0, -8
	s_sub_i32 s33, s84, s0
	s_ashr_i32 s97, s96, 31
	s_add_u32 s29, s26, 0x1500000
	s_addc_u32 s83, s27, 0
	s_add_u32 s8, s26, 0x30400000
	s_addc_u32 s9, s27, 0
	s_sub_i32 s0, 0x83f, s84
	s_ashr_i32 s1, s0, 31
	s_lshr_b32 s1, s1, 28
	s_add_i32 s1, s0, s1
	s_and_b32 s2, s1, 0xfffff0
	s_sub_i32 s4, s0, s2
	s_lshl_b32 s0, s1, 3
	s_and_b32 s0, s0, 0xffffff80
	s_ashr_i32 s1, s0, 31
	s_lshl_b64 s[2:3], s[0:1], 13
	s_add_u32 s6, s8, s2
	v_writelane_b32 v252, s8, 0
	s_addc_u32 s7, s9, s3
	s_lshl_b32 s4, s4, 8
	s_ashr_i32 s5, s4, 31
	s_lshl_b64 s[4:5], s[4:5], 1
	s_add_u32 s6, s6, s4
	s_addc_u32 s7, s7, s5
	v_writelane_b32 v252, s9, 1
	s_add_u32 s8, s6, 0x20000
	s_addc_u32 s9, s7, 0
	v_writelane_b32 v252, s8, 32
	s_mov_b32 s28, s12
	s_movk_i32 s93, 0x16c
	v_writelane_b32 v252, s9, 33
	s_add_u32 s8, s6, 0x40000
	s_addc_u32 s9, s7, 0
	v_writelane_b32 v252, s8, 34
	v_readlane_b32 s25, v251, 3
	v_mov_b32_e32 v203, 0
	v_writelane_b32 v252, s9, 35
	s_add_u32 s8, s6, 0x60000
	s_addc_u32 s9, s7, 0
	v_writelane_b32 v252, s8, 36
	v_mov_b32_e32 v0, 0x260
	v_mov_b32_e32 v236, 0x40666666
	v_writelane_b32 v252, s9, 37
	s_add_u32 s8, s6, 0x80000
	s_addc_u32 s9, s7, 0
	v_writelane_b32 v252, s8, 38
	v_mbcnt_hi_u32_b32 v237, -1, v69
	s_movk_i32 s89, 0x4000
	v_writelane_b32 v252, s9, 39
	s_add_u32 s8, s6, 0xa0000
	s_addc_u32 s9, s7, 0
	v_writelane_b32 v252, s8, 40
	s_mov_b32 s77, 0xffff0000
	s_mov_b32 s51, 0xc0666666
	v_writelane_b32 v252, s9, 41
	s_add_u32 s8, s6, 0xc0000
	s_addc_u32 s9, s7, 0
	v_writelane_b32 v252, s8, 42
	s_movk_i32 s53, 0x7fff
	s_mov_b32 s67, 0x2801000
	v_writelane_b32 v252, s9, 43
	s_add_u32 s8, s6, 0xe0000
	v_writelane_b32 v252, s6, 44
	s_addc_u32 s9, s7, 0
	s_add_u32 s78, s26, 0x28000000
	v_writelane_b32 v252, s7, 45
	s_addc_u32 s79, s27, 0
	s_lshl_b64 s[0:1], s[0:1], 3
	v_writelane_b32 v252, s8, 46
	s_add_u32 s0, s29, s0
	s_addc_u32 s1, s83, s1
	v_writelane_b32 v252, s9, 47
	v_writelane_b32 v252, s0, 48
	s_mov_b32 s87, 0
	s_mov_b64 s[80:81], 0x80
	v_writelane_b32 v252, s1, 49
	s_add_u32 s0, s78, s2
	s_addc_u32 s1, s79, s3
	s_add_u32 s0, s0, s4
	s_addc_u32 s1, s1, s5
	s_add_u32 s2, s0, 0x20000
	s_addc_u32 s3, s1, 0
	v_writelane_b32 v252, s2, 50
	s_mov_b32 s74, 0x3e8e38e4
	s_mov_b32 s76, 0x3f35102b
	v_writelane_b32 v252, s3, 51
	s_add_u32 s2, s0, 0x40000
	s_addc_u32 s3, s1, 0
	v_writelane_b32 v252, s2, 52
	s_mov_b32 s46, 0x406095ad
	s_mov_b32 s48, 0xc0f75c23
	v_writelane_b32 v252, s3, 53
	s_add_u32 s2, s0, 0x60000
	s_addc_u32 s3, s1, 0
	v_writelane_b32 v252, s2, 54
	s_mov_b32 s50, 0x4122bf24
	s_mov_b32 s92, 0xc1124633
	v_writelane_b32 v252, s3, 55
	s_add_u32 s2, s0, 0x80000
	s_addc_u32 s3, s1, 0
	v_writelane_b32 v252, s2, 56
	s_mov_b32 s82, 0x40c2591c
	s_mov_b32 s52, 0xc04719c3
	v_writelane_b32 v252, s3, 57
	s_add_u32 s2, s0, 0xa0000
	s_addc_u32 s3, s1, 0
	v_writelane_b32 v252, s2, 58
	s_mov_b32 s54, 0x3fb7d0d5
	s_waitcnt lgkmcnt(0)
	v_writelane_b32 v252, s3, 59
	s_add_u32 s2, s0, 0xc0000
	s_addc_u32 s3, s1, 0
	v_writelane_b32 v252, s2, 60
	s_barrier
	s_nop 0
	v_writelane_b32 v252, s3, 61
	s_add_u32 s2, s0, 0xe0000
	v_writelane_b32 v252, s0, 62
	s_addc_u32 s3, s1, 0
	v_writelane_b32 v253, s2, 0
	s_cmpk_lt_i32 s84, 0x200
	v_writelane_b32 v252, s1, 63
	v_writelane_b32 v253, s3, 1
	s_cselect_b64 s[0:1], -1, 0
	s_lshl_b32 s2, s33, 6
	s_add_u32 s68, s26, 0x46e00000
	s_addc_u32 s69, s27, 0
	v_writelane_b32 v253, s0, 2
	s_cmpk_lt_i32 s84, 0x80
	s_nop 0
	v_writelane_b32 v253, s1, 3
	s_cselect_b64 s[0:1], -1, 0
	v_writelane_b32 v253, s0, 4
	s_and_b32 s30, s84, 7
	s_nop 0
	v_writelane_b32 v253, s1, 5
	s_bfe_u32 s0, s84, 0x10003
	s_or_b32 s3, s0, 64
	s_lshl_b32 s0, s84, 6
	s_and_b32 s4, s0, 0xfffffc00
	s_lshl_b32 s0, s3, 21
	s_ashr_i32 s5, s4, 31
	s_lshl_b32 s1, s30, 21
	s_add_u32 s0, s78, s0
	v_writelane_b32 v253, s1, 6
	s_addc_u32 s1, s79, 0
	s_add_u32 s0, s0, s4
	s_addc_u32 s1, s1, s5
	s_add_u32 s6, s0, 0x100000
	v_writelane_b32 v253, s0, 7
	s_addc_u32 s7, s1, 0
	s_cmpk_lt_i32 s84, 0xb58
	v_writelane_b32 v253, s1, 8
	v_writelane_b32 v253, s6, 9
	s_cselect_b64 s[0:1], -1, 0
	s_cmpk_lt_i32 s84, 0xb0
	v_writelane_b32 v253, s7, 10
	v_writelane_b32 v253, s0, 11
	s_cselect_b64 s[6:7], -1, 0
	s_nop 0
	v_writelane_b32 v253, s1, 12
	s_mul_i32 s0, s3, 0x2c0000
	v_writelane_b32 v253, s3, 13
	s_add_u32 s0, s78, s0
	v_writelane_b32 v253, s6, 14
	s_addc_u32 s1, s79, 0
	s_add_u32 s0, s0, s4
	v_writelane_b32 v253, s7, 15
	v_writelane_b32 v253, s4, 16
	s_addc_u32 s1, s1, s5
	v_writelane_b32 v253, s5, 17
	s_add_u32 s4, s0, 0x160000
	v_writelane_b32 v253, s0, 18
	s_addc_u32 s5, s1, 0
	s_movk_i32 s3, 0x43
	v_writelane_b32 v253, s1, 19
	s_add_u32 s0, s26, 0x30000000
	s_addc_u32 s1, s27, 0
	v_writelane_b32 v253, s4, 20
	v_writelane_b32 v252, s0, 26
	s_cmpk_lt_i32 s84, 0x210
	v_writelane_b32 v253, s5, 21
	v_writelane_b32 v252, s1, 27
	s_cselect_b64 s[0:1], -1, 0
	v_writelane_b32 v253, s0, 22
	s_cmpk_lt_i32 s56, 0x200
	v_readlane_b32 s8, v252, 10
	v_writelane_b32 v253, s1, 23
	s_cselect_b64 s[0:1], -1, 0
	s_ashr_i32 s4, s56, 2
	v_writelane_b32 v253, s0, 24
	s_ashr_i32 s5, s4, 31
	s_ashr_i32 s57, s56, 31
	v_writelane_b32 v253, s1, 25
	s_lshl_b64 s[0:1], s[4:5], 17
	v_writelane_b32 v253, s0, 26
	v_readlane_b32 s20, v252, 22
	v_readlane_b32 s21, v252, 23
	v_writelane_b32 v253, s1, 27
	s_lshl_b64 s[0:1], s[56:57], 18
	s_add_u32 s0, s78, s0
	s_addc_u32 s1, s79, s1
	s_add_u32 s6, s0, 0x20000
	v_writelane_b32 v253, s0, 28
	s_addc_u32 s7, s1, 0
	s_cmpk_lt_i32 s56, 0x80
	v_writelane_b32 v253, s1, 29
	v_writelane_b32 v253, s6, 30
	s_cselect_b64 s[0:1], -1, 0
	v_readlane_b32 s14, v252, 16
	v_writelane_b32 v253, s7, 31
	v_writelane_b32 v253, s0, 32
	v_readlane_b32 s15, v252, 17
	v_readlane_b32 s16, v252, 18
	v_writelane_b32 v253, s1, 33
	s_add_u32 s0, s26, 0x34400000
	s_addc_u32 s1, s27, 0
	v_writelane_b32 v253, s0, 34
	s_add_u32 s64, s26, 0x34800000
	s_addc_u32 s65, s27, 0
	v_writelane_b32 v253, s1, 35
	s_mov_b32 s0, s4
	v_writelane_b32 v253, s0, 36
	v_readlane_b32 s9, v252, 11
	v_readlane_b32 s10, v252, 12
	v_writelane_b32 v253, s1, 37
	s_lshl_b64 s[0:1], s[4:5], 18
	v_writelane_b32 v253, s0, 38
	v_readlane_b32 s11, v252, 13
	v_readlane_b32 s13, v252, 15
	v_writelane_b32 v253, s1, 39
	s_add_u32 s0, s20, 0x4000
	s_addc_u32 s1, s21, 0
	v_writelane_b32 v253, s0, 40
	s_cmp_lt_i32 s33, 0
	v_readlane_b32 s12, v252, 14
	v_writelane_b32 v253, s1, 41
	s_cselect_b64 s[0:1], -1, 0
	v_writelane_b32 v253, s0, 42
	v_readlane_b32 s17, v252, 19
	v_readlane_b32 s18, v252, 20
	v_writelane_b32 v253, s1, 43
	s_and_b64 s[0:1], s[0:1], exec
	s_movk_i32 s1, 0x109
	s_cselect_b32 s1, s1, 0x108
	s_mul_i32 s0, s33, 0x41
	s_mul_i32 s1, s33, s1
	s_cselect_b32 s0, s0, s2
	s_cselect_b32 s2, s93, 0x16b
	s_cselect_b32 s3, s3, 0x42
	s_add_i32 s1, s1, s31
	s_ashr_i32 s4, s1, 31
	s_lshr_b32 s4, s4, 24
	s_add_i32 s4, s1, s4
	s_and_b32 s5, s4, 0xffffff00
	s_add_i32 s0, s0, s31
	s_sub_i32 s5, s1, s5
	s_ashr_i32 s1, s0, 31
	s_lshr_b32 s1, s1, 26
	s_add_i32 s1, s0, s1
	s_and_b32 s6, s1, 0xffc0
	s_sub_i32 s0, s0, s6
	s_bfe_i32 s6, s0, 0x80000
	s_bfe_u32 s6, s6, 0x3000c
	s_add_i32 s6, s0, s6
	s_and_b32 s7, s6, 0xf8
	s_sub_i32 s0, s0, s7
	s_ashr_i32 s1, s1, 6
	s_bfe_i32 s6, s6, 0x80000
	s_lshl_b32 s1, s1, 3
	s_sext_i32_i16 s6, s6
	s_sext_i32_i8 s0, s0
	s_add_i32 s14, s1, s0
	s_lshr_b32 s0, s6, 3
	s_ashr_i32 s4, s4, 8
	s_bfe_i64 s[0:1], s[0:1], 0x100000
	s_lshl_b32 s4, s4, 3
	s_lshl_b64 s[0:1], s[0:1], 21
	s_sub_i32 s7, 0x42, s4
	s_ashr_i32 s15, s14, 31
	v_writelane_b32 v253, s0, 44
	s_min_u32 s7, s7, 8
	s_ashr_i32 s16, s6, 3
	v_writelane_b32 v253, s1, 45
	s_lshl_b64 s[0:1], s[14:15], 21
	s_add_u32 s0, s78, s0
	s_addc_u32 s1, s79, s1
	s_add_u32 s8, s0, 0x100000
	v_writelane_b32 v253, s0, 46
	s_addc_u32 s9, s1, 0
	s_mov_b32 s10, s14
	v_writelane_b32 v253, s1, 47
	s_mul_i32 s0, s33, s2
	s_add_i32 s0, s0, s31
	s_mul_hi_i32 s1, s0, 0x2e8ba2e9
	s_lshr_b32 s2, s1, 31
	s_ashr_i32 s1, s1, 6
	s_add_i32 s1, s1, s2
	v_writelane_b32 v253, s8, 48
	s_mul_i32 s2, s1, 0x160
	s_lshl_b32 s6, s1, 3
	v_writelane_b32 v253, s9, 49
	s_sub_i32 s2, s0, s2
	s_sub_i32 s0, 0x42, s6
	s_min_u32 s8, s0, 8
	v_writelane_b32 v253, s10, 50
	s_mul_i32 s1, s14, 0x2c0000
	s_mul_hi_i32 s0, s14, 0x2c0000
	v_writelane_b32 v253, s11, 51
	s_add_u32 s10, s78, s1
	s_addc_u32 s11, s79, s0
	s_add_u32 s0, s10, 0x160000
	v_writelane_b32 v253, s10, 52
	s_addc_u32 s1, s11, 0
	v_cvt_f32_ubyte0_e32 v2, s7
	v_writelane_b32 v253, s11, 53
	v_writelane_b32 v253, s0, 54
	v_cvt_f32_i32_e32 v1, s5
	v_rcp_iflag_f32_e32 v3, v2
	v_writelane_b32 v253, s1, 55
	s_mul_i32 s0, s33, s3
	s_add_i32 s0, s0, s31
	s_ashr_i32 s1, s0, 31
	s_lshr_b32 s1, s1, 26
	s_add_i32 s1, s0, s1
	s_and_b32 s3, s1, 0xffffffc0
	s_sub_i32 s9, s0, s3
	s_ashr_i32 s0, s1, 6
	s_lshl_b32 s10, s0, 3
	v_mul_f32_e32 v3, v1, v3
	s_sub_i32 s0, 0x42, s10
	v_trunc_f32_e32 v3, v3
	s_min_u32 s11, s0, 8
	s_ashr_i32 s0, s5, 30
	v_fma_f32 v1, -v3, v2, v1
	s_or_b32 s3, s0, 1
	v_cmp_ge_f32_e64 s[0:1], |v1|, v2
	v_cvt_i32_f32_e32 v1, v3
	s_and_b64 s[0:1], s[0:1], exec
	s_cselect_b32 s0, s3, 0
	v_writelane_b32 v253, s33, 56
	v_readfirstlane_b32 s1, v1
	s_add_i32 s13, s1, s0
	s_mul_i32 s0, s13, s7
	s_abs_i32 s7, s96
	v_cvt_f32_u32_e32 v1, s7
	s_sub_i32 s0, s5, s0
	s_sext_i32_i16 s0, s0
	v_writelane_b32 v253, s31, 57
	v_rcp_iflag_f32_e32 v1, v1
	s_add_i32 s0, s4, s0
	v_writelane_b32 v253, s0, 58
	s_sub_i32 s0, 0, s7
	v_mul_f32_e32 v1, 0x4f7ffffe, v1
	v_cvt_u32_f32_e32 v1, v1
	v_cvt_f32_ubyte0_e32 v2, s8
	v_rcp_iflag_f32_e32 v3, v2
	v_readlane_b32 s19, v252, 21
	v_readfirstlane_b32 s1, v1
	s_mul_i32 s0, s0, s1
	s_mul_hi_u32 s0, s1, s0
	s_add_i32 s14, s1, s0
	s_mul_hi_u32 s0, s14, 0x840
	s_mul_i32 s0, s0, s7
	s_sub_i32 s0, 0x840, s0
	s_sub_i32 s1, s0, s7
	s_cmp_ge_u32 s0, s7
	s_cselect_b32 s0, s1, s0
	s_sub_i32 s1, s0, s7
	s_cmp_ge_u32 s0, s7
	s_cselect_b32 s0, s1, s0
	s_sub_i32 s1, s96, s0
	s_sub_i32 s0, s84, s0
	v_cvt_f32_i32_e32 v1, s2
	s_cmp_gt_i32 s0, -1
	s_cselect_b64 s[4:5], -1, 0
	v_writelane_b32 v253, s4, 59
	s_lshl_b32 s0, s0, 3
	v_mul_f32_e32 v3, v1, v3
	v_writelane_b32 v253, s5, 60
	v_writelane_b32 v253, s0, 61
	s_lshl_b32 s0, s1, 3
	v_trunc_f32_e32 v3, v3
	v_writelane_b32 v253, s0, 62
	s_ashr_i32 s0, s2, 30
	v_fma_f32 v1, -v3, v2, v1
	s_or_b32 s3, s0, 1
	v_cmp_ge_f32_e64 s[0:1], |v1|, v2
	v_cvt_i32_f32_e32 v1, v3
	s_and_b64 s[0:1], s[0:1], exec
	s_cselect_b32 s0, s3, 0
	v_cvt_f32_ubyte0_e32 v2, s11
	v_readfirstlane_b32 s1, v1
	s_add_i32 s0, s1, s0
	s_mul_i32 s1, s0, s8
	s_sub_i32 s1, s2, s1
	s_sext_i32_i16 s1, s1
	s_bfe_i64 s[2:3], s[0:1], 0x100000
	s_lshl_b64 s[2:3], s[2:3], 20
	s_add_i32 s4, s6, s1
	v_writelane_b32 v253, s2, 63
	s_ashr_i32 s5, s4, 31
	s_mul_hi_u32 s1, s14, 0xb58
	v_writelane_b32 v254, s3, 0
	s_mov_b32 s2, s4
	v_writelane_b32 v254, s2, 1
	s_mul_i32 s1, s1, s7
	v_cvt_f32_i32_e32 v1, s9
	v_writelane_b32 v254, s3, 2
	s_lshl_b64 s[2:3], s[4:5], 20
	s_add_u32 s2, s42, s2
	s_addc_u32 s3, s43, s3
	s_add_u32 s4, s2, 0x80000
	v_writelane_b32 v254, s2, 3
	s_addc_u32 s5, s3, 0
	s_sub_i32 s1, 0xb58, s1
	v_writelane_b32 v254, s3, 4
	s_sub_i32 s2, s1, s7
	s_cmp_ge_u32 s1, s7
	s_cselect_b32 s1, s2, s1
	s_sub_i32 s2, s1, s7
	v_rcp_iflag_f32_e32 v3, v2
	s_cmp_ge_u32 s1, s7
	s_cselect_b32 s1, s2, s1
	s_sub_i32 s2, s96, s1
	s_sub_i32 s3, s84, s1
	v_writelane_b32 v254, s4, 5
	s_cmp_gt_i32 s3, -1
	v_mul_f32_e32 v3, v1, v3
	v_writelane_b32 v254, s5, 6
	s_cselect_b64 s[4:5], -1, 0
	v_trunc_f32_e32 v3, v3
	v_writelane_b32 v254, s4, 7
	s_lshl_b32 s8, s2, 3
	s_ashr_i32 s2, s9, 30
	v_fma_f32 v1, -v3, v2, v1
	v_writelane_b32 v254, s5, 8
	s_lshl_b32 s6, s3, 3
	s_or_b32 s4, s2, 1
	v_cmp_ge_f32_e64 s[2:3], |v1|, v2
	v_cvt_i32_f32_e32 v1, v3
	s_and_b64 s[2:3], s[2:3], exec
	s_cselect_b32 s2, s4, 0
	s_sext_i32_i16 s0, s0
	v_readfirstlane_b32 s3, v1
	s_add_i32 s2, s3, s2
	s_mul_i32 s3, s2, s11
	s_sub_i32 s3, s9, s3
	s_sext_i32_i8 s3, s3
	s_bfe_i64 s[4:5], s[2:3], 0x80000
	s_lshl_b64 s[4:5], s[4:5], 20
	s_add_i32 s10, s10, s3
	v_writelane_b32 v254, s4, 9
	s_ashr_i32 s11, s10, 31
	v_readlane_b32 s22, v252, 24
	v_writelane_b32 v254, s5, 10
	s_mov_b32 s4, s10
	v_writelane_b32 v254, s4, 11
	v_readlane_b32 s23, v252, 25
	s_mov_b32 s12, s29
	v_writelane_b32 v254, s5, 12
	s_lshl_b64 s[4:5], s[10:11], 20
	s_add_u32 s4, s42, s4
	v_writelane_b32 v254, s0, 13
	s_sext_i32_i8 s0, s2
	s_addc_u32 s5, s43, s5
	v_writelane_b32 v254, s0, 14
	s_add_u32 s2, s4, 0x80000
	v_writelane_b32 v254, s4, 15
	s_mul_hi_u32 s0, s14, 0x210
	s_addc_u32 s3, s5, 0
	v_writelane_b32 v254, s5, 16
	s_mul_i32 s0, s0, s7
	v_writelane_b32 v254, s2, 17
	s_sub_i32 s0, 0x210, s0
	v_mov_b32_e32 v1, 1
	v_writelane_b32 v254, s3, 18
	s_sub_i32 s2, s0, s7
	s_cmp_ge_u32 s0, s7
	s_cselect_b32 s0, s2, s0
	s_sub_i32 s2, s0, s7
	s_cmp_ge_u32 s0, s7
	s_cselect_b32 s0, s2, s0
	s_sub_i32 s2, s96, s0
	s_sub_i32 s0, s84, s0
	s_cmp_gt_i32 s0, -1
	s_cselect_b64 s[4:5], -1, 0
	v_writelane_b32 v254, s4, 19
	s_lshl_b32 s0, s0, 3
	s_nop 0
	v_writelane_b32 v254, s5, 20
	v_writelane_b32 v254, s0, 21
	s_lshl_b32 s0, s2, 3
	v_writelane_b32 v254, s0, 22
	s_mul_hi_u32 s0, s14, 0x420
	s_mul_i32 s0, s0, s7
	s_sub_i32 s0, 0x420, s0
	s_sub_i32 s2, s0, s7
	s_cmp_ge_u32 s0, s7
	s_cselect_b32 s0, s2, s0
	s_sub_i32 s2, s0, s7
	s_cmp_ge_u32 s0, s7
	s_cselect_b32 s0, s2, s0
	s_sub_i32 s2, s96, s0
	s_sub_i32 s0, s84, s0
	s_cmp_gt_i32 s0, -1
	s_cselect_b64 s[4:5], -1, 0
	v_writelane_b32 v254, s4, 23
	s_lshl_b32 s0, s0, 3
	s_add_i32 s0, s0, 0xba80
	v_writelane_b32 v254, s5, 24
	v_writelane_b32 v254, s0, 25
	s_lshl_b32 s0, s2, 3
	v_writelane_b32 v254, s0, 26
	v_writelane_b32 v254, s6, 27
	s_add_i32 s0, s6, 0xe480
	s_ashr_i32 s95, s94, 31
	v_writelane_b32 v254, s0, 28
	s_ashr_i32 s0, s28, 31
	v_writelane_b32 v254, s0, 29
	s_sub_i32 s0, 0x83f, s84
	s_lshl_b32 s0, s0, 8
	s_lshl_b64 s[2:3], s[94:95], 3
	v_writelane_b32 v254, s0, 30
	s_sub_i32 s0, 0x83f, s84
	s_lshl_b32 s0, s0, 7
	v_writelane_b32 v252, s2, 28
	v_writelane_b32 v254, s0, 31
	s_lshl_b32 s0, s56, 5
	v_writelane_b32 v252, s3, 29
	s_lshl_b64 s[2:3], s[94:95], 9
	s_lshl_b32 s75, s96, 4
	v_writelane_b32 v254, s0, 32
	s_lshl_b32 s0, s96, 5
	v_writelane_b32 v252, s2, 8
	v_writelane_b32 v254, s0, 33
	s_nop 0
	v_writelane_b32 v252, s3, 9
	s_add_u32 s2, s26, 0x44c00100
	s_addc_u32 s3, s27, 0
	v_writelane_b32 v254, s2, 34
	s_lshl_b32 s0, s56, 4
	s_lshl_b64 s[62:63], s[96:97], 17
	v_writelane_b32 v254, s3, 35
	s_add_u32 s2, s26, 0x40c00200
	v_writelane_b32 v254, s0, 36
	s_addc_u32 s3, s27, 0
	v_writelane_b32 v254, s2, 37
	s_lshl_b32 s0, s1, 3
	s_lshl_b32 s1, s84, 3
	v_writelane_b32 v254, s3, 38
	s_sub_i32 s0, s1, s0
	s_sext_i32_i16 s1, s13
	v_writelane_b32 v254, s1, 39
	s_add_i32 s0, s0, 0xcc80
	v_writelane_b32 v254, s0, 40
	v_writelane_b32 v254, s30, 41
	s_mul_i32 s0, s30, 0x2c0000
	v_writelane_b32 v254, s0, 42
	s_mul_hi_i32 s0, s16, 0x2c0000
	v_writelane_b32 v254, s0, 43
	v_writelane_b32 v254, s16, 44
	s_mul_i32 s0, s16, 0x2c0000
	v_writelane_b32 v254, s0, 45
	s_lshl_b64 s[0:1], s[96:97], 18
	v_writelane_b32 v254, s0, 46
	v_writelane_b32 v251, s62, 62
	s_movk_i32 s13, 0x2c00
	v_writelane_b32 v254, s1, 47
	s_add_u32 s0, s24, 0x1000
	v_writelane_b32 v254, s0, 48
	s_addc_u32 s0, s25, 0
	v_writelane_b32 v254, s0, 49
	v_writelane_b32 v254, s28, 50
	s_add_i32 s0, s28, s94
	v_writelane_b32 v254, s0, 51
	s_add_i32 s0, 0, 0x20160
	v_writelane_b32 v254, s0, 52
	s_add_i32 s0, 0, 0x20164
	v_writelane_b32 v254, s0, 53
	s_add_i32 s0, 0, 0x1a800
	v_writelane_b32 v254, s0, 54
	s_add_i32 s0, 0, 0x1aa00
	v_writelane_b32 v254, s0, 55
	s_add_i32 s0, 0, 0x10800
	v_writelane_b32 v254, s0, 56
	s_add_i32 s0, 0, 0x1a900
	v_writelane_b32 v254, s0, 57
	s_mov_b32 s0, 0
	v_writelane_b32 v254, s0, 58
	s_lshl_b64 s[0:1], s[94:95], 13
	v_writelane_b32 v254, s0, 60
	v_writelane_b32 v251, s63, 63
	s_nop 0
	v_writelane_b32 v254, s1, 61
	s_lshl_b64 s[0:1], s[94:95], 12
	v_writelane_b32 v254, s0, 62
	s_mov_b32 s95, s8
	s_nop 0
	v_writelane_b32 v254, s1, 63
	s_mov_b64 s[0:1], -1
	v_writelane_b32 v255, s0, 0
	s_nop 1
	v_writelane_b32 v255, s1, 1
	v_writelane_b32 v255, s83, 2
	v_writelane_b32 v255, s95, 3
	v_writelane_b32 v255, s72, 4
	s_nop 1
	v_writelane_b32 v255, s73, 5
	s_branch .LBB0_383

.LBB0_623:
	s_or_b64 exec, exec, s[36:37]
	v_mov_b32_e32 v3, v56
	s_waitcnt lgkmcnt(0)
	s_barrier
	v_readlane_b32 s2, v252, 44
	v_lshlrev_b32_e32 v5, 4, v3
	v_lshlrev_b32_e32 v2, 8, v3
	v_and_b32_e32 v4, 0x1f0, v5
	s_movk_i32 s1, 0xe000
	s_waitcnt vmcnt(0)
	v_readlane_b32 s3, v252, 45
	v_and_or_b32 v129, v2, s1, v4
	s_nop 4
	global_load_dwordx4 v[18:21], v129, s[2:3]
	v_readlane_b32 s2, v252, 32
	v_readlane_b32 s3, v252, 33
	s_nop 4
	global_load_dwordx4 v[22:25], v129, s[2:3]
	v_readlane_b32 s2, v252, 34
	v_readlane_b32 s3, v252, 35
	s_nop 4
	global_load_dwordx4 v[26:29], v129, s[2:3]
	v_readlane_b32 s2, v252, 36
	v_readlane_b32 s3, v252, 37
	s_nop 4
	global_load_dwordx4 v[30:33], v129, s[2:3]
	v_readlane_b32 s2, v252, 38
	v_readlane_b32 s3, v252, 39
	s_nop 4
	global_load_dwordx4 v[34:37], v129, s[2:3]
	v_readlane_b32 s2, v252, 40
	v_readlane_b32 s3, v252, 41
	s_nop 4
	global_load_dwordx4 v[38:41], v129, s[2:3]
	v_readlane_b32 s2, v252, 42
	v_readfirstlane_b32 s0, v3
	v_readlane_b32 s3, v252, 43
	s_ashr_i32 s0, s0, 6
	s_nop 4
	global_load_dwordx4 v[42:45], v129, s[2:3]
	v_readlane_b32 s2, v252, 46
	v_bfe_u32 v128, v3, 2, 4
	s_lshl_b32 s4, s0, 5
	v_lshlrev_b32_e32 v7, 3, v3
	v_readlane_b32 s3, v252, 47
	v_lshl_add_u32 v6, v128, 12, s4
	v_and_b32_e32 v2, 24, v7
	s_nop 4
	global_load_dwordx4 v[46:49], v129, s[2:3]
	v_readlane_b32 s2, v252, 48
	v_or_b32_e32 v8, v6, v2
	v_and_b32_e32 v6, 0x7f, v3
	v_readlane_b32 s3, v252, 49
	v_lshlrev_b32_e32 v131, 3, v6
	s_nop 4
	global_load_dwordx2 v[118:119], v131, s[2:3]
	v_readlane_b32 s2, v252, 62
	v_readlane_b32 s3, v252, 63
	v_lshlrev_b32_e32 v130, 1, v8
	s_nop 4
	global_load_dwordx4 v[78:81], v130, s[2:3]
	v_readlane_b32 s2, v252, 50
	v_readlane_b32 s3, v252, 51
	s_nop 4
	global_load_dwordx4 v[74:77], v130, s[2:3]
	v_readlane_b32 s2, v252, 52
	v_readlane_b32 s3, v252, 53
	s_nop 4
	global_load_dwordx4 v[70:73], v130, s[2:3]
	v_readlane_b32 s2, v252, 54
	v_readlane_b32 s3, v252, 55
	s_nop 4
	global_load_dwordx4 v[66:69], v130, s[2:3]
	v_readlane_b32 s2, v252, 56
	v_readlane_b32 s3, v252, 57
	s_nop 4
	global_load_dwordx4 v[62:65], v130, s[2:3]
	v_readlane_b32 s2, v252, 58
	v_readlane_b32 s3, v252, 59
	s_nop 4
	global_load_dwordx4 v[58:61], v130, s[2:3]
	v_readlane_b32 s2, v252, 60
	v_readlane_b32 s3, v252, 61
	s_nop 4
	global_load_dwordx4 v[54:57], v130, s[2:3]
	v_readlane_b32 s2, v253, 0
	v_readlane_b32 s3, v253, 1
	s_nop 4
	global_load_dwordx4 v[50:53], v130, s[2:3]
	s_waitcnt vmcnt(8)
	s_and_b64 vcc, exec, s[72:73]
	s_cbranch_vccz .LBB0_633
	v_readlane_b32 s5, v254, 58
	s_lshl_b32 s1, s5, 19
	v_readlane_b32 s2, v252, 30
	v_readlane_b32 s3, v252, 31
	s_add_u32 s2, s2, s1
	s_addc_u32 s3, s3, 0
	s_lshl_b32 s86, s5, 12
	v_readlane_b32 s16, v251, 14
	s_lshl_b64 s[6:7], s[86:87], 2
	v_readlane_b32 s24, v251, 22
	v_readlane_b32 s25, v251, 23
	s_add_u32 s10, s24, s6
	s_addc_u32 s11, s25, s7
	s_lshl_b32 s86, s5, 11
	v_readlane_b32 s30, v251, 28
	s_lshl_b64 s[8:9], s[86:87], 2
	v_readlane_b32 s31, v251, 29
	s_add_u32 s8, s30, s8
	v_and_b32_e32 v8, 63, v3
	v_readlane_b32 s26, v251, 24
	s_addc_u32 s9, s31, s9
	v_readlane_b32 s27, v251, 25
	s_add_u32 s6, s26, s6
	v_lshrrev_b32_e32 v13, 5, v8
	v_ashrrev_i32_e32 v8, 4, v3
	s_addc_u32 s7, s27, s7
	s_mulk_i32 s0, 0x2400
	v_ashrrev_i32_e32 v9, 31, v8
	s_ashr_i32 s5, s4, 31
	s_add_i32 s14, s0, 0
	v_lshlrev_b64 v[10:11], 8, v[8:9]
	s_lshl_b64 s[0:1], s[4:5], 2
	v_lshl_add_u64 v[10:11], s[2:3], 0, v[10:11]
	v_and_b32_e32 v7, 0x78, v7
	s_add_u32 s2, s10, s0
	v_lshlrev_b32_e32 v202, 1, v7
	s_addc_u32 s3, s11, s1
	v_and_b32_e32 v12, 31, v3
	v_lshl_add_u64 v[120:121], v[10:11], 0, v[202:203]
	v_lshlrev_b32_e32 v202, 2, v6
	s_add_u32 s0, s6, s0
	v_lshl_add_u64 v[122:123], s[8:9], 0, v[202:203]
	v_lshlrev_b32_e32 v202, 2, v12
	s_addc_u32 s1, s7, s1
	v_lshl_add_u64 v[126:127], s[0:1], 0, v[202:203]
	s_movk_i32 s1, 0x80
	v_lshl_add_u64 v[124:125], s[2:3], 0, v[202:203]
	v_cmp_gt_i32_e64 s[2:3], s1, v3
	s_lshl_b32 s1, s4, 2
	v_readlane_b32 s7, v254, 55
	s_add_i32 s1, s7, s1
	v_and_b32_e32 v5, 0xf0, v5
	s_add_i32 s0, 0, 0x12000
	v_readlane_b32 s6, v254, 54
	v_add_u32_e32 v133, s1, v202
	v_readlane_b32 s1, v254, 56
	v_lshlrev_b32_e32 v7, 4, v13
	v_add_u32_e32 v14, 0x200, v3
	v_add_u32_e32 v16, 0x400, v3
	v_add_u32_e32 v82, 0x600, v3
	v_add_u32_e32 v5, s0, v5
	v_lshl_add_u32 v132, v3, 2, s6
	v_lshl_add_u32 v134, v3, 3, s1
	v_add_u32_e32 v9, s0, v7
	s_movk_i32 s0, 0x110
	v_lshrrev_b32_e32 v15, 4, v14
	v_lshrrev_b32_e32 v17, 4, v16
	v_lshrrev_b32_e32 v83, 4, v82
	v_ashrrev_i32_e32 v84, 5, v3
	v_add_u32_e32 v85, 0x800, v3
	v_add_u32_e32 v86, 0xa00, v3
	v_add_u32_e32 v87, 0xc00, v3
	v_add_u32_e32 v3, 0xe00, v3
	v_or_b32_e32 v6, s4, v12
	v_mul_lo_u32 v8, v8, s0
	v_mul_lo_u32 v15, v15, s0
	v_mul_lo_u32 v17, v17, s0
	v_mul_lo_u32 v83, v83, s0
	s_movk_i32 s0, 0x210
	v_ashrrev_i32_e32 v14, 5, v14
	v_ashrrev_i32_e32 v16, 5, v16
	v_ashrrev_i32_e32 v82, 5, v82
	v_ashrrev_i32_e32 v85, 5, v85
	v_ashrrev_i32_e32 v86, 5, v86
	v_ashrrev_i32_e32 v87, 5, v87
	v_ashrrev_i32_e32 v3, 5, v3
	v_lshl_add_u32 v136, v13, 6, s1
	v_mul_u32_u24_e32 v88, 0x1080, v13
	v_lshl_or_b32 v89, v13, 3, 1
	v_mov_b32_e32 v91, 0xc60
	v_mov_b32_e32 v92, 0x2940
	v_mov_b32_e32 v93, 0x4620
	v_mov_b32_e32 v94, 0x6300
	v_mul_u32_u24_e32 v95, 0x240, v13
	v_lshl_or_b32 v13, v13, 2, 1
	v_readlane_b32 s17, v251, 15
	v_readlane_b32 s18, v251, 16
	v_add_u32_e32 v4, 0, v4
	v_lshl_add_u32 v135, v6, 2, s7
	v_lshl_add_u32 v6, v6, 1, 0
	v_add_u32_e32 v10, s14, v202
	v_lshl_add_u32 v11, v2, 2, s14
	v_mul_lo_u32 v84, v84, s0
	v_mul_lo_u32 v14, v14, s0
	v_mul_lo_u32 v16, v16, s0
	v_mul_lo_u32 v82, v82, s0
	v_mul_lo_u32 v85, v85, s0
	v_mul_lo_u32 v86, v86, s0
	v_mul_lo_u32 v87, v87, s0
	v_mul_lo_u32 v3, v3, s0
	v_mul_u32_u24_e32 v90, 0x210, v89
	v_mad_u32_u24 v91, v89, s0, v91
	v_mad_u32_u24 v92, v89, s0, v92
	v_mad_u32_u24 v93, v89, s0, v93
	v_mad_u32_u24 v89, v89, s0, v94
	v_mul_u32_u24_e32 v94, 0x90, v128
	v_mul_u32_u24_e32 v12, 0x110, v12
	v_lshlrev_b32_e32 v96, 2, v13
	v_mul_u32_u24_e32 v13, 0x90, v13
	v_or_b32_e32 v97, 8, v7
	v_or_b32_e32 v98, 12, v7
	v_or_b32_e32 v99, 32, v7
	v_or_b32_e32 v100, 36, v7
	v_or_b32_e32 v101, 40, v7
	v_or_b32_e32 v102, 44, v7
	v_or_b32_e32 v103, 64, v7
	v_or_b32_e32 v104, 0x44, v7
	v_or_b32_e32 v105, 0x48, v7
	v_or_b32_e32 v106, 0x4c, v7
	v_or_b32_e32 v107, 0x60, v7
	v_or_b32_e32 v108, 0x64, v7
	v_or_b32_e32 v109, 0x68, v7
	v_or_b32_e32 v110, 0x6c, v7
	v_or_b32_e32 v111, 0x80, v7
	v_or_b32_e32 v112, 0x84, v7
	v_or_b32_e32 v113, 0x88, v7
	v_or_b32_e32 v114, 0x8c, v7
	v_or_b32_e32 v115, 0xa0, v7
	v_or_b32_e32 v116, 0xa4, v7
	v_or_b32_e32 v117, 0xa8, v7
	v_or_b32_e32 v202, 0xac, v7
	v_or_b32_e32 v204, 0xc0, v7
	v_or_b32_e32 v205, 0xc4, v7
	v_or_b32_e32 v206, 0xc8, v7
	v_or_b32_e32 v207, 0xcc, v7
	v_or_b32_e32 v223, 0xe0, v7
	v_or_b32_e32 v224, 0xe4, v7
	v_or_b32_e32 v225, 0xe8, v7
	v_or_b32_e32 v226, 0xec, v7
	v_readlane_b32 s0, v254, 57
	v_add_u32_e32 v137, 0x180, v136
	v_add_u32_e32 v138, 0x190, v136
	v_add_u32_e32 v139, 0x1a0, v136
	v_add_u32_e32 v140, 0x1b0, v136
	v_add_u32_e32 v141, 0x200, v136
	v_add_u32_e32 v142, 0x210, v136
	v_add_u32_e32 v143, 0x220, v136
	v_add_u32_e32 v144, 0x230, v136
	v_add_u32_e32 v145, 0x280, v136
	v_add_u32_e32 v146, 0x290, v136
	v_add_u32_e32 v147, 0x2a0, v136
	v_add_u32_e32 v148, 0x2b0, v136
	v_add_u32_e32 v149, 0x300, v136
	v_add_u32_e32 v150, 0x310, v136
	v_add_u32_e32 v151, 0x320, v136
	v_add_u32_e32 v152, 0x330, v136
	v_add_u32_e32 v153, 0x380, v136
	v_add_u32_e32 v154, 0x390, v136
	v_add_u32_e32 v155, 0x3a0, v136
	v_add_u32_e32 v156, 0x3b0, v136
	v_add_u32_e32 v157, s6, v7
	v_add_u32_e32 v158, s6, v96
	v_add_u32_e32 v159, s6, v97
	v_add_u32_e32 v160, s6, v98
	v_add_u32_e32 v161, s6, v99
	v_add_u32_e32 v162, s6, v100
	v_add_u32_e32 v163, s6, v101
	v_add_u32_e32 v164, s6, v102
	v_add_u32_e32 v165, s6, v103
	v_add_u32_e32 v166, s6, v104
	v_add_u32_e32 v167, s6, v105
	v_add_u32_e32 v168, s6, v106
	v_add_u32_e32 v169, s6, v107
	v_add_u32_e32 v170, s6, v108
	v_add_u32_e32 v171, s6, v109
	v_add_u32_e32 v172, s6, v110
	v_add_u32_e32 v173, s6, v111
	v_add_u32_e32 v174, s6, v112
	v_add_u32_e32 v175, s6, v113
	v_add_u32_e32 v176, s6, v114
	v_add_u32_e32 v177, s6, v115
	v_add_u32_e32 v178, s6, v116
	v_add_u32_e32 v179, s6, v117
	v_add_u32_e32 v180, s6, v202
	v_add_u32_e32 v181, s6, v204
	v_add_u32_e32 v182, s6, v205
	v_add_u32_e32 v183, s6, v206
	v_add_u32_e32 v184, s6, v207
	v_add_u32_e32 v185, s6, v223
	v_add_u32_e32 v186, s6, v224
	v_add_u32_e32 v187, s6, v225
	v_add_u32_e32 v188, s6, v226
	v_add_u32_e32 v189, s0, v7
	v_add_u32_e32 v190, s0, v96
	v_add_u32_e32 v191, s0, v97
	v_add_u32_e32 v192, s0, v98
	v_add_u32_e32 v193, s0, v99
	v_add_u32_e32 v194, s0, v100
	v_add_u32_e32 v195, s0, v101
	v_add_u32_e32 v196, s0, v102
	v_add_u32_e32 v197, s0, v103
	v_add_u32_e32 v198, s0, v104
	v_add_u32_e32 v199, s0, v105
	v_add_u32_e32 v200, s0, v106
	v_add_u32_e32 v201, s0, v107
	v_add_u32_e32 v208, s0, v108
	v_add_u32_e32 v209, s0, v109
	v_add_u32_e32 v210, s0, v110
	v_add_u32_e32 v211, s0, v111
	v_add_u32_e32 v212, s0, v112
	v_add_u32_e32 v213, s0, v113
	v_add_u32_e32 v214, s0, v114
	v_add_u32_e32 v215, s0, v115
	v_add_u32_e32 v216, s0, v116
	v_add_u32_e32 v217, s0, v117
	v_add_u32_e32 v218, s0, v202
	v_add_u32_e32 v219, s0, v204
	v_add_u32_e32 v220, s0, v205
	v_add_u32_e32 v221, s0, v206
	v_add_u32_e32 v222, s0, v207
	v_add_u32_e32 v223, s0, v223
	v_add_u32_e32 v224, s0, v224
	v_add_u32_e32 v225, s0, v225
	v_add_u32_e32 v226, s0, v226
	s_lshl_b32 s14, s96, 8
	s_lshl_b32 s15, s96, 7
	s_mov_b32 s18, -1
	v_add_u32_e32 v227, v5, v8
	v_add_u32_e32 v228, v5, v15
	v_add_u32_e32 v229, v5, v17
	v_add_u32_e32 v230, v5, v83
	v_add_u32_e32 v231, v4, v84
	v_add_u32_e32 v232, v4, v14
	v_add_u32_e32 v233, v4, v16
	v_add_u32_e32 v238, v4, v82
	v_add_u32_e32 v239, v4, v85
	v_add_u32_e32 v240, v4, v86
	v_add_u32_e32 v241, v4, v87
	v_add_u32_e32 v242, v4, v3
	v_add_u32_e32 v243, v6, v88
	v_add_u32_e32 v244, v6, v90
	v_add_u32_e32 v245, v6, v91
	v_add_u32_e32 v246, v6, v92
	v_add_u32_e32 v247, v6, v93
	v_add_u32_e32 v248, v6, v89
	v_lshlrev_b32_e32 v202, 1, v2
	v_add_u32_e32 v249, v9, v12
	v_add_u32_e32 v250, v10, v95
	v_add_u32_e32 v204, v10, v13
	v_add_u32_e32 v205, v11, v94
	v_readlane_b32 s16, v254, 31
	v_readlane_b32 s17, v254, 30
	s_sub_i32 s10, 0x83f, s84
	s_mov_b32 s57, 0x20000
	s_mov_b32 s88, 0x40000
	v_readlane_b32 s19, v251, 17
	v_readlane_b32 s20, v251, 18
	v_readlane_b32 s21, v251, 19
	v_readlane_b32 s22, v251, 20
	v_readlane_b32 s23, v251, 21
	v_readlane_b32 s28, v251, 26
	v_readlane_b32 s29, v251, 27

.LBB0_629:
	s_and_saveexec_b64 s[6:7], s[2:3]
	ds_write_b64 v134, v[118:119]
	s_or_b64 exec, exec, s[6:7]
	s_sub_i32 s19, s10, s96
	s_cmp_gt_i32 s19, -1
	s_cselect_b64 s[6:7], -1, 0
	s_and_b64 s[0:1], s[6:7], exec
	s_cselect_b32 s0, s19, s10
	s_ashr_i32 s1, s0, 31
	s_lshr_b32 s1, s1, 28
	s_add_i32 s1, s0, s1
	s_and_b32 s8, s1, 0xfffff0
	s_sub_i32 s10, s0, s8
	s_lshl_b32 s0, s1, 3
	s_and_b32 s0, s0, 0xffffff80
	s_ashr_i32 s1, s0, 31
	s_lshl_b64 s[8:9], s[0:1], 13
	v_readlane_b32 s22, v252, 0
	v_readlane_b32 s23, v252, 1
	s_add_u32 s21, s22, s8
	s_addc_u32 s23, s23, s9
	s_lshl_b32 s10, s10, 8
	s_ashr_i32 s11, s10, 31
	s_lshl_b64 s[10:11], s[10:11], 1
	s_add_u32 s22, s21, s10
	s_addc_u32 s23, s23, s11
	s_add_u32 s24, s22, 0x20000
	ds_write_b128 v231, v[18:21]
	ds_write_b128 v232, v[22:25]
	ds_write_b128 v233, v[26:29]
	ds_write_b128 v238, v[30:33]
	ds_write_b128 v239, v[34:37]
	ds_write_b128 v240, v[38:41]
	ds_write_b128 v241, v[42:45]
	ds_write_b128 v242, v[46:49]
	s_waitcnt lgkmcnt(0)
	s_barrier
	s_nop 4
	global_load_dwordx4 v[18:21], v129, s[22:23]
	s_addc_u32 s25, s23, 0
	s_nop 4
	global_load_dwordx4 v[22:25], v129, s[24:25]
	s_add_u32 s24, s22, 0x40000
	s_addc_u32 s25, s23, 0
	s_nop 4
	global_load_dwordx4 v[26:29], v129, s[24:25]
	s_add_u32 s24, s22, 0x60000
	s_addc_u32 s25, s23, 0
	s_nop 4
	global_load_dwordx4 v[30:33], v129, s[24:25]
	s_add_u32 s24, s22, 0x80000
	s_addc_u32 s25, s23, 0
	s_nop 4
	global_load_dwordx4 v[34:37], v129, s[24:25]
	s_add_u32 s24, s22, 0xa0000
	s_addc_u32 s25, s23, 0
	s_nop 4
	global_load_dwordx4 v[38:41], v129, s[24:25]
	s_add_u32 s24, s22, 0xc0000
	s_addc_u32 s25, s23, 0
	s_add_u32 s22, s22, 0xe0000
	s_nop 4
	global_load_dwordx4 v[42:45], v129, s[24:25]
	s_addc_u32 s23, s23, 0
	s_lshl_b64 s[0:1], s[0:1], 3
	s_nop 4
	global_load_dwordx4 v[46:49], v129, s[22:23]
	s_add_u32 s0, s12, s0
	s_addc_u32 s1, s83, s1
	s_nop 4
	global_load_dwordx2 v[118:119], v131, s[0:1]
	v_add_u32_e32 v6, 16, v136
	ds_read_b32 v110, v135
	ds_read_b32 v112, v133 offset:1024
	ds_read_b128 v[2:5], v136
	ds_read_u16 v82, v243
	ds_read_u16 v86, v244
	ds_read_b128 v[6:9], v6
	ds_read_u16 v83, v244 offset:528
	ds_read_u16 v87, v244 offset:1056
	v_add_u32_e32 v10, 32, v136
	v_add_u32_e32 v14, 48, v136
	ds_read_b128 v[10:13], v10
	ds_read_u16 v88, v244 offset:1584
	ds_read_u16 v89, v244 offset:2112
	ds_read_b128 v[14:17], v14
	ds_read_u16 v90, v244 offset:2640
	ds_read_u16 v91, v245
	s_waitcnt lgkmcnt(0)
	v_lshlrev_b32_e32 v83, 16, v83
	v_lshlrev_b32_e32 v82, 16, v82
	v_mov_b32_e32 v84, v2
	v_mov_b32_e32 v85, v6
	v_pk_add_f32 v[82:83], v[82:83], v[84:85] neg_lo:[0,1] neg_hi:[0,1]
	v_mov_b32_e32 v6, v3
	v_pk_mul_f32 v[2:3], v[6:7], v[82:83]
	v_lshlrev_b32_e32 v7, 16, v87
	v_lshlrev_b32_e32 v6, 16, v86
	v_mov_b32_e32 v82, v4
	v_mov_b32_e32 v83, v8
	v_pk_add_f32 v[6:7], v[6:7], v[82:83] neg_lo:[0,1] neg_hi:[0,1]
	v_mov_b32_e32 v8, v5
	v_pk_mul_f32 v[4:5], v[8:9], v[6:7]
	v_lshlrev_b32_e32 v7, 16, v90
	v_lshlrev_b32_e32 v6, 16, v88
	v_mov_b32_e32 v8, v10
	v_mov_b32_e32 v9, v14
	v_pk_add_f32 v[6:7], v[6:7], v[8:9] neg_lo:[0,1] neg_hi:[0,1]
	v_mov_b32_e32 v14, v11
	v_lshlrev_b32_e32 v9, 16, v91
	v_lshlrev_b32_e32 v8, 16, v89
	v_mov_b32_e32 v10, v12
	v_mov_b32_e32 v11, v16
	v_pk_add_f32 v[8:9], v[8:9], v[10:11] neg_lo:[0,1] neg_hi:[0,1]
	v_mov_b32_e32 v16, v13
	v_pk_mul_f32 v[8:9], v[16:17], v[8:9]
	v_pk_fma_f32 v[4:5], v[110:111], v[4:5], v[112:113] op_sel_hi:[0,1,0]
	v_pk_mul_f32 v[6:7], v[14:15], v[6:7]
	v_pk_fma_f32 v[8:9], v[110:111], v[8:9], v[112:113] op_sel_hi:[0,1,0]
	v_pk_fma_f32 v[2:3], v[110:111], v[2:3], v[112:113] op_sel_hi:[0,1,0]
	v_pk_fma_f32 v[6:7], v[110:111], v[6:7], v[112:113] op_sel_hi:[0,1,0]
	v_bfe_u32 v10, v9, 16, 1
	v_bfe_u32 v12, v5, 16, 1
	v_bfe_u32 v11, v8, 16, 1
	v_bfe_u32 v13, v4, 16, 1
	v_add3_u32 v5, v5, v12, s53
	v_add3_u32 v9, v9, v10, s53
	v_bfe_u32 v10, v2, 16, 1
	v_bfe_u32 v12, v6, 16, 1
	v_add3_u32 v4, v4, v13, s53
	v_add3_u32 v8, v8, v11, s53
	v_bfe_u32 v11, v3, 16, 1
	v_bfe_u32 v13, v7, 16, 1
	v_add3_u32 v6, v6, v12, s53
	v_add3_u32 v2, v2, v10, s53
	v_add3_u32 v7, v7, v13, s53
	v_add3_u32 v3, v3, v11, s53
	v_lshrrev_b32_e32 v2, 16, v2
	v_lshrrev_b32_e32 v6, 16, v6
	v_lshrrev_b32_e32 v3, 16, v3
	v_lshrrev_b32_e32 v7, 16, v7
	v_and_or_b32 v84, v8, s77, v6
	v_and_or_b32 v82, v4, s77, v2
	v_add_u32_e32 v2, 0x80, v136
	v_add_u32_e32 v6, 0x90, v136
	v_and_or_b32 v85, v9, s77, v7
	v_and_or_b32 v83, v5, s77, v3
	ds_read_b128 v[2:5], v2
	ds_read_u16 v86, v245 offset:4752
	ds_read_u16 v90, v245 offset:5280
	ds_read_b128 v[6:9], v6
	ds_read_u16 v87, v245 offset:5808
	ds_read_u16 v91, v245 offset:6336
	v_add_u32_e32 v10, 0xa0, v136
	v_add_u32_e32 v14, 0xb0, v136
	ds_read_b128 v[10:13], v10
	ds_read_u16 v92, v245 offset:6864
	ds_read_u16 v93, v246
	ds_read_b128 v[14:17], v14
	ds_read_u16 v94, v246 offset:528
	ds_read_u16 v95, v246 offset:1056
	s_waitcnt lgkmcnt(0)
	v_lshlrev_b32_e32 v87, 16, v87
	v_lshlrev_b32_e32 v86, 16, v86
	v_mov_b32_e32 v88, v2
	v_mov_b32_e32 v89, v6
	v_pk_add_f32 v[86:87], v[86:87], v[88:89] neg_lo:[0,1] neg_hi:[0,1]
	v_mov_b32_e32 v6, v3
	v_pk_mul_f32 v[2:3], v[6:7], v[86:87]
	v_lshlrev_b32_e32 v7, 16, v91
	v_lshlrev_b32_e32 v6, 16, v90
	v_mov_b32_e32 v86, v4
	v_mov_b32_e32 v87, v8
	v_pk_add_f32 v[6:7], v[6:7], v[86:87] neg_lo:[0,1] neg_hi:[0,1]
	v_mov_b32_e32 v8, v5
	v_pk_mul_f32 v[4:5], v[8:9], v[6:7]
	v_lshlrev_b32_e32 v7, 16, v94
	v_lshlrev_b32_e32 v6, 16, v92
	v_mov_b32_e32 v8, v10
	v_mov_b32_e32 v9, v14
	v_pk_add_f32 v[6:7], v[6:7], v[8:9] neg_lo:[0,1] neg_hi:[0,1]
	v_mov_b32_e32 v14, v11
	v_lshlrev_b32_e32 v9, 16, v95
	v_lshlrev_b32_e32 v8, 16, v93
	v_mov_b32_e32 v10, v12
	v_mov_b32_e32 v11, v16
	v_pk_add_f32 v[8:9], v[8:9], v[10:11] neg_lo:[0,1] neg_hi:[0,1]
	v_mov_b32_e32 v16, v13
	v_pk_mul_f32 v[8:9], v[16:17], v[8:9]
	v_pk_fma_f32 v[4:5], v[110:111], v[4:5], v[112:113] op_sel_hi:[0,1,0]
	v_pk_mul_f32 v[6:7], v[14:15], v[6:7]
	v_pk_fma_f32 v[8:9], v[110:111], v[8:9], v[112:113] op_sel_hi:[0,1,0]
	v_pk_fma_f32 v[2:3], v[110:111], v[2:3], v[112:113] op_sel_hi:[0,1,0]
	v_pk_fma_f32 v[6:7], v[110:111], v[6:7], v[112:113] op_sel_hi:[0,1,0]
	v_bfe_u32 v10, v9, 16, 1
	v_bfe_u32 v12, v5, 16, 1
	v_bfe_u32 v11, v8, 16, 1
	v_bfe_u32 v13, v4, 16, 1
	v_add3_u32 v5, v5, v12, s53
	v_add3_u32 v9, v9, v10, s53
	v_bfe_u32 v10, v2, 16, 1
	v_bfe_u32 v12, v6, 16, 1
	v_add3_u32 v4, v4, v13, s53
	v_add3_u32 v8, v8, v11, s53
	v_bfe_u32 v11, v3, 16, 1
	v_bfe_u32 v13, v7, 16, 1
	v_add3_u32 v6, v6, v12, s53
	v_add3_u32 v2, v2, v10, s53
	v_add3_u32 v7, v7, v13, s53
	v_add3_u32 v3, v3, v11, s53
	v_lshrrev_b32_e32 v2, 16, v2
	v_lshrrev_b32_e32 v6, 16, v6
	v_lshrrev_b32_e32 v3, 16, v3
	v_lshrrev_b32_e32 v7, 16, v7
	v_and_or_b32 v88, v8, s77, v6
	v_and_or_b32 v86, v4, s77, v2
	v_add_u32_e32 v2, 0x100, v136
	v_add_u32_e32 v6, 0x110, v136
	v_and_or_b32 v89, v9, s77, v7
	v_and_or_b32 v87, v5, s77, v3
	ds_read_b128 v[2:5], v2
	ds_read_u16 v90, v246 offset:5808
	ds_read_u16 v94, v246 offset:6336
	ds_read_b128 v[6:9], v6
	ds_read_u16 v91, v246 offset:6864
	ds_read_u16 v95, v247
	v_add_u32_e32 v10, 0x120, v136
	v_add_u32_e32 v14, 0x130, v136
	ds_read_b128 v[10:13], v10
	ds_read_u16 v96, v247 offset:528
	ds_read_u16 v97, v247 offset:1056
	ds_read_b128 v[14:17], v14
	ds_read_u16 v98, v247 offset:1584
	ds_read_u16 v99, v247 offset:2112
	s_waitcnt lgkmcnt(0)
	v_lshlrev_b32_e32 v91, 16, v91
	v_lshlrev_b32_e32 v90, 16, v90
	v_mov_b32_e32 v92, v2
	v_mov_b32_e32 v93, v6
	v_pk_add_f32 v[90:91], v[90:91], v[92:93] neg_lo:[0,1] neg_hi:[0,1]
	v_mov_b32_e32 v6, v3
	v_pk_mul_f32 v[2:3], v[6:7], v[90:91]
	v_lshlrev_b32_e32 v7, 16, v95
	v_lshlrev_b32_e32 v6, 16, v94
	v_mov_b32_e32 v90, v4
	v_mov_b32_e32 v91, v8
	v_pk_add_f32 v[6:7], v[6:7], v[90:91] neg_lo:[0,1] neg_hi:[0,1]
	v_mov_b32_e32 v8, v5
	v_pk_mul_f32 v[4:5], v[8:9], v[6:7]
	v_lshlrev_b32_e32 v7, 16, v98
	v_lshlrev_b32_e32 v6, 16, v96
	v_mov_b32_e32 v8, v10
	v_mov_b32_e32 v9, v14
	v_pk_add_f32 v[6:7], v[6:7], v[8:9] neg_lo:[0,1] neg_hi:[0,1]
	v_mov_b32_e32 v14, v11
	v_lshlrev_b32_e32 v9, 16, v99
	v_lshlrev_b32_e32 v8, 16, v97
	v_mov_b32_e32 v10, v12
	v_mov_b32_e32 v11, v16
	v_pk_add_f32 v[8:9], v[8:9], v[10:11] neg_lo:[0,1] neg_hi:[0,1]
	v_mov_b32_e32 v16, v13
	v_pk_mul_f32 v[8:9], v[16:17], v[8:9]
	v_pk_fma_f32 v[4:5], v[110:111], v[4:5], v[112:113] op_sel_hi:[0,1,0]
	v_pk_mul_f32 v[6:7], v[14:15], v[6:7]
	v_pk_fma_f32 v[8:9], v[110:111], v[8:9], v[112:113] op_sel_hi:[0,1,0]
	v_pk_fma_f32 v[2:3], v[110:111], v[2:3], v[112:113] op_sel_hi:[0,1,0]
	v_pk_fma_f32 v[6:7], v[110:111], v[6:7], v[112:113] op_sel_hi:[0,1,0]
	v_bfe_u32 v10, v9, 16, 1
	v_bfe_u32 v11, v8, 16, 1
	v_bfe_u32 v12, v5, 16, 1
	v_bfe_u32 v13, v4, 16, 1
	v_add3_u32 v4, v4, v13, s53
	v_add3_u32 v5, v5, v12, s53
	v_add3_u32 v8, v8, v11, s53
	v_add3_u32 v9, v9, v10, s53
	v_bfe_u32 v10, v2, 16, 1
	v_bfe_u32 v11, v3, 16, 1
	v_bfe_u32 v12, v6, 16, 1
	v_bfe_u32 v13, v7, 16, 1
	v_add3_u32 v7, v7, v13, s53
	v_add3_u32 v6, v6, v12, s53
	v_add3_u32 v3, v3, v11, s53
	v_add3_u32 v2, v2, v10, s53
	v_lshrrev_b32_e32 v2, 16, v2
	v_lshrrev_b32_e32 v3, 16, v3
	v_lshrrev_b32_e32 v6, 16, v6
	v_lshrrev_b32_e32 v7, 16, v7
	v_and_or_b32 v93, v9, s77, v7
	v_and_or_b32 v92, v8, s77, v6
	v_and_or_b32 v91, v5, s77, v3
	v_and_or_b32 v90, v4, s77, v2
	ds_read_b128 v[2:5], v137
	ds_read_u16 v94, v247 offset:6864
	ds_read_u16 v98, v248
	ds_read_b128 v[6:9], v138
	ds_read_u16 v95, v248 offset:528
	ds_read_u16 v99, v248 offset:1056
	ds_read_b128 v[10:13], v139
	ds_read_u16 v100, v248 offset:1584
	ds_read_u16 v101, v248 offset:2112
	ds_read_b128 v[14:17], v140
	ds_read_u16 v102, v248 offset:2640
	ds_read_u16 v103, v248 offset:3168
	s_waitcnt lgkmcnt(0)
	v_lshlrev_b32_e32 v95, 16, v95
	v_lshlrev_b32_e32 v94, 16, v94
	v_mov_b32_e32 v96, v2
	v_mov_b32_e32 v97, v6
	v_pk_add_f32 v[94:95], v[94:95], v[96:97] neg_lo:[0,1] neg_hi:[0,1]
	v_mov_b32_e32 v6, v3
	v_pk_mul_f32 v[2:3], v[6:7], v[94:95]
	v_lshlrev_b32_e32 v7, 16, v99
	v_lshlrev_b32_e32 v6, 16, v98
	v_mov_b32_e32 v94, v4
	v_mov_b32_e32 v95, v8
	v_pk_add_f32 v[6:7], v[6:7], v[94:95] neg_lo:[0,1] neg_hi:[0,1]
	v_mov_b32_e32 v8, v5
	v_pk_mul_f32 v[4:5], v[8:9], v[6:7]
	v_lshlrev_b32_e32 v7, 16, v102
	v_lshlrev_b32_e32 v6, 16, v100
	v_mov_b32_e32 v8, v10
	v_mov_b32_e32 v9, v14
	v_pk_add_f32 v[6:7], v[6:7], v[8:9] neg_lo:[0,1] neg_hi:[0,1]
	v_mov_b32_e32 v14, v11
	v_lshlrev_b32_e32 v9, 16, v103
	v_lshlrev_b32_e32 v8, 16, v101
	v_mov_b32_e32 v10, v12
	v_mov_b32_e32 v11, v16
	v_pk_add_f32 v[8:9], v[8:9], v[10:11] neg_lo:[0,1] neg_hi:[0,1]
	v_mov_b32_e32 v16, v13
	v_pk_mul_f32 v[8:9], v[16:17], v[8:9]
	v_pk_fma_f32 v[4:5], v[110:111], v[4:5], v[112:113] op_sel_hi:[0,1,0]
	v_pk_mul_f32 v[6:7], v[14:15], v[6:7]
	v_pk_fma_f32 v[8:9], v[110:111], v[8:9], v[112:113] op_sel_hi:[0,1,0]
	v_pk_fma_f32 v[2:3], v[110:111], v[2:3], v[112:113] op_sel_hi:[0,1,0]
	v_pk_fma_f32 v[6:7], v[110:111], v[6:7], v[112:113] op_sel_hi:[0,1,0]
	v_bfe_u32 v10, v9, 16, 1
	v_bfe_u32 v11, v8, 16, 1
	v_bfe_u32 v12, v5, 16, 1
	v_bfe_u32 v13, v4, 16, 1
	v_add3_u32 v4, v4, v13, s53
	v_add3_u32 v5, v5, v12, s53
	v_add3_u32 v8, v8, v11, s53
	v_add3_u32 v9, v9, v10, s53
	v_bfe_u32 v10, v2, 16, 1
	v_bfe_u32 v11, v3, 16, 1
	v_bfe_u32 v12, v6, 16, 1
	v_bfe_u32 v13, v7, 16, 1
	v_add3_u32 v7, v7, v13, s53
	v_add3_u32 v6, v6, v12, s53
	v_add3_u32 v3, v3, v11, s53
	v_add3_u32 v2, v2, v10, s53
	v_lshrrev_b32_e32 v2, 16, v2
	v_lshrrev_b32_e32 v3, 16, v3
	v_lshrrev_b32_e32 v6, 16, v6
	v_lshrrev_b32_e32 v7, 16, v7
	v_and_or_b32 v97, v9, s77, v7
	v_and_or_b32 v96, v8, s77, v6
	v_and_or_b32 v95, v5, s77, v3
	v_and_or_b32 v94, v4, s77, v2
	ds_read_b128 v[2:5], v141
	ds_read_u16 v98, v248 offset:7920
	ds_read_u16 v102, v248 offset:8448
	ds_read_b128 v[6:9], v142
	ds_read_u16 v99, v248 offset:8976
	ds_read_u16 v103, v248 offset:9504
	ds_read_b128 v[10:13], v143
	ds_read_u16 v104, v248 offset:10032
	ds_read_u16 v105, v248 offset:10560
	ds_read_b128 v[14:17], v144
	ds_read_u16 v106, v248 offset:11088
	ds_read_u16 v107, v248 offset:11616
	s_waitcnt lgkmcnt(0)
	v_lshlrev_b32_e32 v99, 16, v99
	v_lshlrev_b32_e32 v98, 16, v98
	v_mov_b32_e32 v100, v2
	v_mov_b32_e32 v101, v6
	v_pk_add_f32 v[98:99], v[98:99], v[100:101] neg_lo:[0,1] neg_hi:[0,1]
	v_mov_b32_e32 v6, v3
	v_pk_mul_f32 v[2:3], v[6:7], v[98:99]
	v_lshlrev_b32_e32 v7, 16, v103
	v_lshlrev_b32_e32 v6, 16, v102
	v_mov_b32_e32 v98, v4
	v_mov_b32_e32 v99, v8
	v_pk_add_f32 v[6:7], v[6:7], v[98:99] neg_lo:[0,1] neg_hi:[0,1]
	v_mov_b32_e32 v8, v5
	v_pk_mul_f32 v[4:5], v[8:9], v[6:7]
	v_lshlrev_b32_e32 v7, 16, v106
	v_lshlrev_b32_e32 v6, 16, v104
	v_mov_b32_e32 v8, v10
	v_mov_b32_e32 v9, v14
	v_pk_add_f32 v[6:7], v[6:7], v[8:9] neg_lo:[0,1] neg_hi:[0,1]
	v_mov_b32_e32 v14, v11
	v_lshlrev_b32_e32 v9, 16, v107
	v_lshlrev_b32_e32 v8, 16, v105
	v_mov_b32_e32 v10, v12
	v_mov_b32_e32 v11, v16
	v_pk_add_f32 v[8:9], v[8:9], v[10:11] neg_lo:[0,1] neg_hi:[0,1]
	v_mov_b32_e32 v16, v13
	v_pk_mul_f32 v[8:9], v[16:17], v[8:9]
	v_pk_fma_f32 v[4:5], v[110:111], v[4:5], v[112:113] op_sel_hi:[0,1,0]
	v_pk_mul_f32 v[6:7], v[14:15], v[6:7]
	v_pk_fma_f32 v[8:9], v[110:111], v[8:9], v[112:113] op_sel_hi:[0,1,0]
	v_pk_fma_f32 v[2:3], v[110:111], v[2:3], v[112:113] op_sel_hi:[0,1,0]
	v_pk_fma_f32 v[6:7], v[110:111], v[6:7], v[112:113] op_sel_hi:[0,1,0]
	v_bfe_u32 v10, v9, 16, 1
	v_bfe_u32 v11, v8, 16, 1
	v_bfe_u32 v12, v5, 16, 1
	v_bfe_u32 v13, v4, 16, 1
	v_add3_u32 v4, v4, v13, s53
	v_add3_u32 v5, v5, v12, s53
	v_add3_u32 v8, v8, v11, s53
	v_add3_u32 v9, v9, v10, s53
	v_bfe_u32 v10, v2, 16, 1
	v_bfe_u32 v11, v3, 16, 1
	v_bfe_u32 v12, v6, 16, 1
	v_bfe_u32 v13, v7, 16, 1
	v_add3_u32 v7, v7, v13, s53
	v_add3_u32 v6, v6, v12, s53
	v_add3_u32 v3, v3, v11, s53
	v_add3_u32 v2, v2, v10, s53
	v_lshrrev_b32_e32 v2, 16, v2
	v_lshrrev_b32_e32 v3, 16, v3
	v_lshrrev_b32_e32 v6, 16, v6
	v_lshrrev_b32_e32 v7, 16, v7
	v_and_or_b32 v101, v9, s77, v7
	v_and_or_b32 v100, v8, s77, v6
	v_and_or_b32 v99, v5, s77, v3
	v_and_or_b32 v98, v4, s77, v2
	ds_read_b128 v[2:5], v145
	ds_read_u16 v102, v248 offset:16368
	ds_read_u16 v106, v248 offset:16896
	ds_read_b128 v[6:9], v146
	ds_read_u16 v103, v248 offset:17424
	ds_read_u16 v107, v248 offset:17952
	ds_read_b128 v[10:13], v147
	ds_read_u16 v108, v248 offset:18480
	ds_read_u16 v109, v248 offset:19008
	ds_read_b128 v[14:17], v148
	ds_read_u16 v111, v248 offset:19536
	ds_read_u16 v113, v248 offset:20064
	s_waitcnt lgkmcnt(0)
	v_lshlrev_b32_e32 v103, 16, v103
	v_lshlrev_b32_e32 v102, 16, v102
	v_mov_b32_e32 v104, v2
	v_mov_b32_e32 v105, v6
	v_pk_add_f32 v[102:103], v[102:103], v[104:105] neg_lo:[0,1] neg_hi:[0,1]
	v_mov_b32_e32 v6, v3
	v_pk_mul_f32 v[2:3], v[6:7], v[102:103]
	v_lshlrev_b32_e32 v7, 16, v107
	v_lshlrev_b32_e32 v6, 16, v106
	v_mov_b32_e32 v102, v4
	v_mov_b32_e32 v103, v8
	v_pk_add_f32 v[6:7], v[6:7], v[102:103] neg_lo:[0,1] neg_hi:[0,1]
	v_mov_b32_e32 v8, v5
	v_pk_mul_f32 v[4:5], v[8:9], v[6:7]
	v_lshlrev_b32_e32 v7, 16, v111
	v_lshlrev_b32_e32 v6, 16, v108
	v_mov_b32_e32 v8, v10
	v_mov_b32_e32 v9, v14
	v_pk_add_f32 v[6:7], v[6:7], v[8:9] neg_lo:[0,1] neg_hi:[0,1]
	v_mov_b32_e32 v14, v11
	v_lshlrev_b32_e32 v9, 16, v113
	v_lshlrev_b32_e32 v8, 16, v109
	v_mov_b32_e32 v10, v12
	v_mov_b32_e32 v11, v16
	v_pk_add_f32 v[8:9], v[8:9], v[10:11] neg_lo:[0,1] neg_hi:[0,1]
	v_mov_b32_e32 v16, v13
	v_pk_mul_f32 v[8:9], v[16:17], v[8:9]
	v_pk_fma_f32 v[4:5], v[110:111], v[4:5], v[112:113] op_sel_hi:[0,1,0]
	v_pk_mul_f32 v[6:7], v[14:15], v[6:7]
	v_pk_fma_f32 v[8:9], v[110:111], v[8:9], v[112:113] op_sel_hi:[0,1,0]
	v_pk_fma_f32 v[2:3], v[110:111], v[2:3], v[112:113] op_sel_hi:[0,1,0]
	v_pk_fma_f32 v[6:7], v[110:111], v[6:7], v[112:113] op_sel_hi:[0,1,0]
	v_bfe_u32 v10, v9, 16, 1
	v_bfe_u32 v11, v8, 16, 1
	v_bfe_u32 v12, v5, 16, 1
	v_bfe_u32 v13, v4, 16, 1
	v_add3_u32 v4, v4, v13, s53
	v_add3_u32 v5, v5, v12, s53
	v_add3_u32 v8, v8, v11, s53
	v_add3_u32 v9, v9, v10, s53
	v_bfe_u32 v10, v2, 16, 1
	v_bfe_u32 v11, v3, 16, 1
	v_bfe_u32 v12, v6, 16, 1
	v_bfe_u32 v13, v7, 16, 1
	v_add3_u32 v7, v7, v13, s53
	v_add3_u32 v6, v6, v12, s53
	v_add3_u32 v3, v3, v11, s53
	v_add3_u32 v2, v2, v10, s53
	v_lshrrev_b32_e32 v2, 16, v2
	v_lshrrev_b32_e32 v3, 16, v3
	v_lshrrev_b32_e32 v6, 16, v6
	v_lshrrev_b32_e32 v7, 16, v7
	v_and_or_b32 v105, v9, s77, v7
	v_and_or_b32 v104, v8, s77, v6
	v_and_or_b32 v103, v5, s77, v3
	v_and_or_b32 v102, v4, s77, v2
	ds_read_b128 v[2:5], v149
	ds_read_u16 v106, v248 offset:24816
	ds_read_u16 v111, v248 offset:25344
	ds_read_b128 v[6:9], v150
	ds_read_u16 v107, v248 offset:25872
	ds_read_u16 v113, v248 offset:26400
	ds_read_b128 v[10:13], v151
	ds_read_u16 v114, v248 offset:26928
	ds_read_u16 v115, v248 offset:27456
	ds_read_b128 v[14:17], v152
	ds_read_u16 v116, v248 offset:27984
	ds_read_u16 v117, v248 offset:28512
	s_waitcnt lgkmcnt(0)
	v_lshlrev_b32_e32 v107, 16, v107
	v_lshlrev_b32_e32 v106, 16, v106
	v_mov_b32_e32 v108, v2
	v_mov_b32_e32 v109, v6
	v_pk_add_f32 v[106:107], v[106:107], v[108:109] neg_lo:[0,1] neg_hi:[0,1]
	v_mov_b32_e32 v6, v3
	v_pk_mul_f32 v[2:3], v[6:7], v[106:107]
	v_lshlrev_b32_e32 v7, 16, v113
	v_lshlrev_b32_e32 v6, 16, v111
	v_mov_b32_e32 v106, v4
	v_mov_b32_e32 v107, v8
	v_pk_add_f32 v[6:7], v[6:7], v[106:107] neg_lo:[0,1] neg_hi:[0,1]
	v_mov_b32_e32 v8, v5
	v_pk_mul_f32 v[4:5], v[8:9], v[6:7]
	v_lshlrev_b32_e32 v7, 16, v116
	v_lshlrev_b32_e32 v6, 16, v114
	v_mov_b32_e32 v8, v10
	v_mov_b32_e32 v9, v14
	v_pk_add_f32 v[6:7], v[6:7], v[8:9] neg_lo:[0,1] neg_hi:[0,1]
	v_mov_b32_e32 v14, v11
	v_lshlrev_b32_e32 v9, 16, v117
	v_lshlrev_b32_e32 v8, 16, v115
	v_mov_b32_e32 v10, v12
	v_mov_b32_e32 v11, v16
	v_pk_add_f32 v[8:9], v[8:9], v[10:11] neg_lo:[0,1] neg_hi:[0,1]
	v_mov_b32_e32 v16, v13
	v_pk_mul_f32 v[8:9], v[16:17], v[8:9]
	v_pk_fma_f32 v[4:5], v[110:111], v[4:5], v[112:113] op_sel_hi:[0,1,0]
	v_pk_mul_f32 v[6:7], v[14:15], v[6:7]
	v_pk_fma_f32 v[8:9], v[110:111], v[8:9], v[112:113] op_sel_hi:[0,1,0]
	v_pk_fma_f32 v[2:3], v[110:111], v[2:3], v[112:113] op_sel_hi:[0,1,0]
	v_pk_fma_f32 v[6:7], v[110:111], v[6:7], v[112:113] op_sel_hi:[0,1,0]
	v_bfe_u32 v10, v9, 16, 1
	v_bfe_u32 v11, v8, 16, 1
	v_bfe_u32 v12, v5, 16, 1
	v_bfe_u32 v13, v4, 16, 1
	v_add3_u32 v4, v4, v13, s53
	v_add3_u32 v5, v5, v12, s53
	v_add3_u32 v8, v8, v11, s53
	v_add3_u32 v9, v9, v10, s53
	v_bfe_u32 v10, v2, 16, 1
	v_bfe_u32 v11, v3, 16, 1
	v_bfe_u32 v12, v6, 16, 1
	v_bfe_u32 v13, v7, 16, 1
	v_add3_u32 v7, v7, v13, s53
	v_add3_u32 v6, v6, v12, s53
	v_add3_u32 v3, v3, v11, s53
	v_add3_u32 v2, v2, v10, s53
	v_lshrrev_b32_e32 v2, 16, v2
	v_lshrrev_b32_e32 v3, 16, v3
	v_lshrrev_b32_e32 v6, 16, v6
	v_lshrrev_b32_e32 v7, 16, v7
	v_and_or_b32 v109, v9, s77, v7
	v_and_or_b32 v108, v8, s77, v6
	v_and_or_b32 v107, v5, s77, v3
	v_and_or_b32 v106, v4, s77, v2
	ds_read_b128 v[6:9], v153
	ds_read_u16 v114, v248 offset:33264
	ds_read_u16 v116, v248 offset:33792
	ds_read_b128 v[10:13], v154
	ds_read_u16 v115, v248 offset:34320
	ds_read_u16 v117, v248 offset:34848
	ds_read_b128 v[2:5], v155
	ds_read_u16 v113, v248 offset:35376
	ds_read_u16 v111, v248 offset:35904
	ds_read_b128 v[14:17], v156
	ds_read_u16 v235, v248 offset:36432
	s_waitcnt lgkmcnt(0)
	v_lshlrev_b32_e32 v115, 16, v115
	v_lshlrev_b32_e32 v114, 16, v114
	v_mov_b32_e32 v206, v6
	v_mov_b32_e32 v207, v10
	v_pk_add_f32 v[114:115], v[114:115], v[206:207] neg_lo:[0,1] neg_hi:[0,1]
	v_lshlrev_b32_e32 v117, 16, v117
	v_lshlrev_b32_e32 v116, 16, v116
	v_mov_b32_e32 v206, v8
	v_mov_b32_e32 v207, v12
	v_pk_add_f32 v[116:117], v[116:117], v[206:207] neg_lo:[0,1] neg_hi:[0,1]
	ds_read_u16 v206, v248 offset:36960
	v_mov_b32_e32 v10, v7
	v_mov_b32_e32 v12, v9
	v_pk_mul_f32 v[6:7], v[10:11], v[114:115]
	v_pk_mul_f32 v[8:9], v[12:13], v[116:117]
	v_lshlrev_b32_e32 v11, 16, v235
	v_lshlrev_b32_e32 v10, 16, v113
	v_mov_b32_e32 v12, v2
	v_mov_b32_e32 v13, v14
	v_pk_add_f32 v[10:11], v[10:11], v[12:13] neg_lo:[0,1] neg_hi:[0,1]
	v_mov_b32_e32 v14, v3
	v_pk_mul_f32 v[2:3], v[14:15], v[10:11]
	s_waitcnt lgkmcnt(0)
	v_lshlrev_b32_e32 v11, 16, v206
	v_lshlrev_b32_e32 v10, 16, v111
	v_mov_b32_e32 v12, v4
	v_mov_b32_e32 v13, v16
	v_pk_fma_f32 v[8:9], v[110:111], v[8:9], v[112:113] op_sel_hi:[0,1,0]
	v_pk_add_f32 v[10:11], v[10:11], v[12:13] neg_lo:[0,1] neg_hi:[0,1]
	v_mov_b32_e32 v16, v5
	v_pk_mul_f32 v[4:5], v[16:17], v[10:11]
	v_bfe_u32 v12, v9, 16, 1
	v_bfe_u32 v13, v8, 16, 1
	s_barrier
	s_waitcnt vmcnt(9)
	v_pk_fma_f32 v[6:7], v[110:111], v[6:7], v[112:113] op_sel_hi:[0,1,0]
	v_pk_fma_f32 v[2:3], v[110:111], v[2:3], v[112:113] op_sel_hi:[0,1,0]
	v_pk_fma_f32 v[4:5], v[110:111], v[4:5], v[112:113] op_sel_hi:[0,1,0]
	v_add3_u32 v110, v8, v13, s53
	v_add3_u32 v111, v9, v12, s53
	ds_read_b128 v[12:15], v249
	v_bfe_u32 v10, v5, 16, 1
	v_bfe_u32 v11, v4, 16, 1
	v_add3_u32 v4, v4, v11, s53
	v_add3_u32 v5, v5, v10, s53
	v_bfe_u32 v9, v7, 16, 1
	v_bfe_u32 v10, v2, 16, 1
	v_bfe_u32 v11, v3, 16, 1
	v_add3_u32 v3, v3, v11, s53
	v_add3_u32 v2, v2, v10, s53
	v_add3_u32 v206, v7, v9, s53
	v_bfe_u32 v8, v6, 16, 1
	v_lshrrev_b32_e32 v2, 16, v2
	v_lshrrev_b32_e32 v3, 16, v3
	ds_read_b128 v[114:117], v249 offset:32
	v_lshrrev_b32_e32 v206, 16, v206
	v_add3_u32 v207, v6, v8, s53
	v_and_or_b32 v113, v5, s77, v3
	v_and_or_b32 v112, v4, s77, v2
	v_and_or_b32 v111, v111, s77, v206
	ds_read_b32 v206, v157
	s_waitcnt lgkmcnt(0)
	v_mfma_f32_32x32x16_bf16 v[2:17], v[12:15], v[82:85], 0
	v_lshrrev_b32_e32 v207, 16, v207
	v_and_or_b32 v110, v110, s77, v207
	s_lshl_b32 s0, s20, 12
	s_sub_i32 s0, s17, s0
	s_ashr_i32 s1, s0, 31
	v_mfma_f32_32x32x16_bf16 v[2:17], v[114:117], v[86:89], v[2:17]
	ds_read_b128 v[114:117], v249 offset:64
	s_waitcnt lgkmcnt(0)
	v_mfma_f32_32x32x16_bf16 v[2:17], v[114:117], v[90:93], v[2:17]
	ds_read_b128 v[114:117], v249 offset:96
	s_waitcnt lgkmcnt(0)
	v_mfma_f32_32x32x16_bf16 v[2:17], v[114:117], v[94:97], v[2:17]
	ds_read_b128 v[114:117], v249 offset:128
	s_waitcnt lgkmcnt(0)
	v_mfma_f32_32x32x16_bf16 v[2:17], v[114:117], v[98:101], v[2:17]
	ds_read_b128 v[114:117], v249 offset:160
	s_waitcnt lgkmcnt(0)
	v_mfma_f32_32x32x16_bf16 v[2:17], v[114:117], v[102:105], v[2:17]
	ds_read_b128 v[114:117], v249 offset:192
	s_waitcnt lgkmcnt(0)
	v_mfma_f32_32x32x16_bf16 v[2:17], v[114:117], v[106:109], v[2:17]
	ds_read_b128 v[114:117], v249 offset:224
	s_waitcnt lgkmcnt(0)
	v_mfma_f32_32x32x16_bf16 v[2:17], v[114:117], v[110:113], v[2:17]
	s_nop 11
	v_add_f32_e32 v2, v2, v206
	ds_write_b32 v250, v2
	ds_read_b32 v2, v158
	s_waitcnt lgkmcnt(0)
	v_add_f32_e32 v2, v3, v2
	ds_write_b32 v204, v2
	ds_read_b32 v2, v159
	s_waitcnt lgkmcnt(0)
	v_add_f32_e32 v2, v4, v2
	ds_write_b32 v204, v2 offset:144
	ds_read_b32 v2, v160
	s_waitcnt lgkmcnt(0)
	v_add_f32_e32 v2, v5, v2
	ds_write_b32 v204, v2 offset:288
	ds_read_b32 v2, v161
	s_waitcnt lgkmcnt(0)
	v_add_f32_e32 v2, v6, v2
	ds_write_b32 v204, v2 offset:1008
	ds_read_b32 v2, v162
	s_waitcnt lgkmcnt(0)
	v_add_f32_e32 v2, v7, v2
	ds_write_b32 v204, v2 offset:1152
	ds_read_b32 v2, v163
	s_waitcnt lgkmcnt(0)
	v_add_f32_e32 v2, v8, v2
	ds_write_b32 v204, v2 offset:1296
	ds_read_b32 v2, v164
	s_waitcnt lgkmcnt(0)
	v_add_f32_e32 v2, v9, v2
	ds_write_b32 v204, v2 offset:1440
	ds_read_b32 v2, v165
	s_waitcnt lgkmcnt(0)
	v_add_f32_e32 v2, v10, v2
	ds_write_b32 v204, v2 offset:2160
	ds_read_b32 v2, v166
	s_waitcnt lgkmcnt(0)
	v_add_f32_e32 v2, v11, v2
	ds_write_b32 v204, v2 offset:2304
	ds_read_b32 v2, v167
	s_waitcnt lgkmcnt(0)
	v_add_f32_e32 v2, v12, v2
	ds_write_b32 v204, v2 offset:2448
	ds_read_b32 v2, v168
	s_waitcnt lgkmcnt(0)
	v_add_f32_e32 v2, v13, v2
	ds_write_b32 v204, v2 offset:2592
	ds_read_b32 v2, v169
	s_waitcnt lgkmcnt(0)
	v_add_f32_e32 v2, v14, v2
	ds_write_b32 v204, v2 offset:3312
	ds_read_b32 v2, v170
	s_waitcnt lgkmcnt(0)
	v_add_f32_e32 v2, v15, v2
	ds_write_b32 v204, v2 offset:3456
	ds_read_b32 v2, v171
	s_waitcnt lgkmcnt(0)
	v_add_f32_e32 v2, v16, v2
	ds_write_b32 v204, v2 offset:3600
	ds_read_b32 v2, v172
	s_waitcnt lgkmcnt(0)
	v_add_f32_e32 v2, v17, v2
	ds_write_b32 v204, v2 offset:3744
	ds_read_b128 v[2:5], v249 offset:8704
	ds_read_b128 v[114:117], v249 offset:8736
	s_waitcnt lgkmcnt(0)
	v_mfma_f32_32x32x16_bf16 v[2:17], v[2:5], v[82:85], 0
	v_mfma_f32_32x32x16_bf16 v[2:17], v[114:117], v[86:89], v[2:17]
	ds_read_b128 v[114:117], v249 offset:8768
	s_waitcnt lgkmcnt(0)
	v_mfma_f32_32x32x16_bf16 v[2:17], v[114:117], v[90:93], v[2:17]
	ds_read_b128 v[114:117], v249 offset:8800
	s_waitcnt lgkmcnt(0)
	v_mfma_f32_32x32x16_bf16 v[2:17], v[114:117], v[94:97], v[2:17]
	ds_read_b128 v[114:117], v249 offset:8832
	s_waitcnt lgkmcnt(0)
	v_mfma_f32_32x32x16_bf16 v[2:17], v[114:117], v[98:101], v[2:17]
	ds_read_b128 v[114:117], v249 offset:8864
	s_waitcnt lgkmcnt(0)
	v_mfma_f32_32x32x16_bf16 v[2:17], v[114:117], v[102:105], v[2:17]
	ds_read_b128 v[114:117], v249 offset:8896
	s_waitcnt lgkmcnt(0)
	v_mfma_f32_32x32x16_bf16 v[2:17], v[114:117], v[106:109], v[2:17]
	ds_read_b128 v[114:117], v249 offset:8928
	ds_read_b32 v206, v173
	s_waitcnt lgkmcnt(0)
	v_mfma_f32_32x32x16_bf16 v[2:17], v[114:117], v[110:113], v[2:17]
	s_nop 11
	v_add_f32_e32 v2, v2, v206
	ds_write_b32 v204, v2 offset:4464
	ds_read_b32 v2, v174
	s_waitcnt lgkmcnt(0)
	v_add_f32_e32 v2, v3, v2
	ds_write_b32 v204, v2 offset:4608
	ds_read_b32 v2, v175
	s_waitcnt lgkmcnt(0)
	v_add_f32_e32 v2, v4, v2
	ds_write_b32 v204, v2 offset:4752
	ds_read_b32 v2, v176
	s_waitcnt lgkmcnt(0)
	v_add_f32_e32 v2, v5, v2
	ds_write_b32 v204, v2 offset:4896
	ds_read_b32 v2, v177
	s_waitcnt lgkmcnt(0)
	v_add_f32_e32 v2, v6, v2
	ds_write_b32 v204, v2 offset:5616
	ds_read_b32 v2, v178
	s_waitcnt lgkmcnt(0)
	v_add_f32_e32 v2, v7, v2
	ds_write_b32 v204, v2 offset:5760
	ds_read_b32 v2, v179
	s_waitcnt lgkmcnt(0)
	v_add_f32_e32 v2, v8, v2
	ds_write_b32 v204, v2 offset:5904
	ds_read_b32 v2, v180
	s_waitcnt lgkmcnt(0)
	v_add_f32_e32 v2, v9, v2
	ds_write_b32 v204, v2 offset:6048
	ds_read_b32 v2, v181
	s_waitcnt lgkmcnt(0)
	v_add_f32_e32 v2, v10, v2
	ds_write_b32 v204, v2 offset:6768
	ds_read_b32 v2, v182
	v_lshlrev_b32_e32 v10, 16, v78
	s_waitcnt lgkmcnt(0)
	v_add_f32_e32 v2, v11, v2
	ds_write_b32 v204, v2 offset:6912
	ds_read_b32 v2, v183
	v_lshlrev_b32_e32 v11, 16, v79
	s_waitcnt lgkmcnt(0)
	v_add_f32_e32 v2, v12, v2
	ds_write_b32 v204, v2 offset:7056
	ds_read_b32 v2, v184
	s_waitcnt lgkmcnt(0)
	v_add_f32_e32 v2, v13, v2
	ds_write_b32 v204, v2 offset:7200
	ds_read_b32 v2, v185
	s_waitcnt lgkmcnt(0)
	v_add_f32_e32 v2, v14, v2
	ds_write_b32 v204, v2 offset:7920
	ds_read_b32 v3, v186
	v_lshl_or_b32 v2, s20, 7, v128
	s_waitcnt lgkmcnt(0)
	v_add_f32_e32 v3, v15, v3
	ds_write_b32 v204, v3 offset:8064
	ds_read_b32 v4, v187
	v_ashrrev_i32_e32 v3, 31, v2
	v_lshlrev_b64 v[2:3], 13, v[2:3]
	v_lshl_add_u64 v[2:3], s[78:79], 0, v[2:3]
	v_lshl_add_u64 v[2:3], s[0:1], 1, v[2:3]
	s_waitcnt lgkmcnt(0)
	v_add_f32_e32 v4, v16, v4
	ds_write_b32 v204, v4 offset:8208
	ds_read_b32 v4, v188
	v_lshl_add_u64 v[6:7], s[4:5], 1, v[2:3]
	v_lshl_add_u64 v[114:115], v[6:7], 0, v[202:203]
	s_mov_b32 s0, 0x60000
	s_waitcnt lgkmcnt(0)
	v_add_f32_e32 v2, v17, v4
	ds_write_b32 v204, v2 offset:8352
	s_waitcnt lgkmcnt(0)
	ds_read_b128 v[2:5], v205
	ds_read_b128 v[6:9], v205 offset:16
	s_waitcnt lgkmcnt(0)
	v_mov_b32_e32 v12, v2
	v_mov_b32_e32 v13, v4
	v_pk_mul_f32 v[10:11], v[12:13], v[10:11]
	v_and_b32_e32 v13, 0xffff0000, v79
	v_and_b32_e32 v12, 0xffff0000, v78
	v_mov_b32_e32 v4, v3
	v_pk_mul_f32 v[2:3], v[4:5], v[12:13]
	v_lshlrev_b32_e32 v5, 16, v81
	v_lshlrev_b32_e32 v4, 16, v80
	v_mov_b32_e32 v12, v6
	v_mov_b32_e32 v13, v8
	v_pk_mul_f32 v[4:5], v[12:13], v[4:5]
	v_and_b32_e32 v13, 0xffff0000, v81
	v_and_b32_e32 v12, 0xffff0000, v80
	v_mov_b32_e32 v8, v7
	v_pk_mul_f32 v[6:7], v[8:9], v[12:13]
	v_bfe_u32 v12, v3, 16, 1
	v_bfe_u32 v8, v7, 16, 1
	v_bfe_u32 v9, v6, 16, 1
	v_bfe_u32 v13, v2, 16, 1
	v_add3_u32 v2, v2, v13, s53
	v_add3_u32 v3, v3, v12, s53
	v_add3_u32 v6, v6, v9, s53
	v_add3_u32 v7, v7, v8, s53
	v_bfe_u32 v8, v10, 16, 1
	v_bfe_u32 v9, v11, 16, 1
	v_bfe_u32 v12, v4, 16, 1
	v_bfe_u32 v13, v5, 16, 1
	v_add3_u32 v5, v5, v13, s53
	v_add3_u32 v4, v4, v12, s53
	v_add3_u32 v9, v11, v9, s53
	v_add3_u32 v8, v10, v8, s53
	v_lshrrev_b32_e32 v8, 16, v8
	v_lshrrev_b32_e32 v9, 16, v9
	v_lshrrev_b32_e32 v4, 16, v4
	v_lshrrev_b32_e32 v5, 16, v5
	v_and_or_b32 v5, v7, s77, v5
	v_and_or_b32 v4, v6, s77, v4
	v_and_or_b32 v3, v3, s77, v9
	v_and_or_b32 v2, v2, s77, v8
	ds_read_b128 v[6:9], v205 offset:2304
	global_store_dwordx4 v[114:115], v[2:5], off
	ds_read_b128 v[2:5], v205 offset:2320
	v_lshlrev_b32_e32 v11, 16, v75
	v_lshlrev_b32_e32 v10, 16, v74
	s_waitcnt lgkmcnt(0)
	v_mov_b32_e32 v12, v6
	v_mov_b32_e32 v13, v8
	v_pk_mul_f32 v[10:11], v[12:13], v[10:11]
	v_and_b32_e32 v13, 0xffff0000, v75
	v_and_b32_e32 v12, 0xffff0000, v74
	v_mov_b32_e32 v8, v7
	v_pk_mul_f32 v[6:7], v[8:9], v[12:13]
	v_lshlrev_b32_e32 v9, 16, v77
	v_lshlrev_b32_e32 v8, 16, v76
	v_mov_b32_e32 v12, v2
	v_mov_b32_e32 v13, v4
	v_pk_mul_f32 v[8:9], v[12:13], v[8:9]
	v_and_b32_e32 v13, 0xffff0000, v77
	v_and_b32_e32 v12, 0xffff0000, v76
	v_mov_b32_e32 v4, v3
	v_pk_mul_f32 v[2:3], v[4:5], v[12:13]
	v_bfe_u32 v12, v7, 16, 1
	v_bfe_u32 v4, v3, 16, 1
	v_bfe_u32 v5, v2, 16, 1
	v_bfe_u32 v13, v6, 16, 1
	v_add3_u32 v6, v6, v13, s53
	v_add3_u32 v7, v7, v12, s53
	v_add3_u32 v2, v2, v5, s53
	v_add3_u32 v3, v3, v4, s53
	v_bfe_u32 v4, v10, 16, 1
	v_bfe_u32 v5, v11, 16, 1
	v_bfe_u32 v12, v8, 16, 1
	v_bfe_u32 v13, v9, 16, 1
	v_add3_u32 v9, v9, v13, s53
	v_add3_u32 v8, v8, v12, s53
	v_add3_u32 v5, v11, v5, s53
	v_add3_u32 v4, v10, v4, s53
	v_lshrrev_b32_e32 v10, 16, v4
	v_lshrrev_b32_e32 v11, 16, v5
	v_lshrrev_b32_e32 v4, 16, v8
	v_lshrrev_b32_e32 v5, 16, v9
	v_and_or_b32 v5, v3, s77, v5
	v_and_or_b32 v4, v2, s77, v4
	v_and_or_b32 v3, v7, s77, v11
	v_and_or_b32 v2, v6, s77, v10
	v_add_co_u32_e32 v10, vcc, s57, v114
	ds_read_b128 v[6:9], v205 offset:4608
	s_nop 0
	v_addc_co_u32_e32 v11, vcc, 0, v115, vcc
	global_store_dwordx4 v[10:11], v[2:5], off
	ds_read_b128 v[2:5], v205 offset:4624
	v_lshlrev_b32_e32 v11, 16, v71
	v_lshlrev_b32_e32 v10, 16, v70
	s_waitcnt lgkmcnt(0)
	v_mov_b32_e32 v12, v6
	v_mov_b32_e32 v13, v8
	v_pk_mul_f32 v[10:11], v[12:13], v[10:11]
	v_and_b32_e32 v13, 0xffff0000, v71
	v_and_b32_e32 v12, 0xffff0000, v70
	v_mov_b32_e32 v8, v7
	v_pk_mul_f32 v[6:7], v[8:9], v[12:13]
	v_lshlrev_b32_e32 v9, 16, v73
	v_lshlrev_b32_e32 v8, 16, v72
	v_mov_b32_e32 v12, v2
	v_mov_b32_e32 v13, v4
	v_pk_mul_f32 v[8:9], v[12:13], v[8:9]
	v_and_b32_e32 v13, 0xffff0000, v73
	v_and_b32_e32 v12, 0xffff0000, v72
	v_mov_b32_e32 v4, v3
	v_pk_mul_f32 v[2:3], v[4:5], v[12:13]
	v_bfe_u32 v12, v7, 16, 1
	v_bfe_u32 v4, v3, 16, 1
	v_bfe_u32 v5, v2, 16, 1
	v_bfe_u32 v13, v6, 16, 1
	v_add3_u32 v6, v6, v13, s53
	v_add3_u32 v7, v7, v12, s53
	v_add3_u32 v2, v2, v5, s53
	v_add3_u32 v3, v3, v4, s53
	v_bfe_u32 v4, v10, 16, 1
	v_bfe_u32 v5, v11, 16, 1
	v_bfe_u32 v12, v8, 16, 1
	v_bfe_u32 v13, v9, 16, 1
	v_add3_u32 v9, v9, v13, s53
	v_add3_u32 v8, v8, v12, s53
	v_add3_u32 v5, v11, v5, s53
	v_add3_u32 v4, v10, v4, s53
	v_lshrrev_b32_e32 v10, 16, v4
	v_lshrrev_b32_e32 v11, 16, v5
	v_lshrrev_b32_e32 v4, 16, v8
	v_lshrrev_b32_e32 v5, 16, v9
	v_and_or_b32 v5, v3, s77, v5
	v_and_or_b32 v4, v2, s77, v4
	v_and_or_b32 v3, v7, s77, v11
	v_and_or_b32 v2, v6, s77, v10
	v_add_co_u32_e32 v10, vcc, s88, v114
	ds_read_b128 v[6:9], v205 offset:6912
	s_nop 0
	v_addc_co_u32_e32 v11, vcc, 0, v115, vcc
	global_store_dwordx4 v[10:11], v[2:5], off
	ds_read_b128 v[2:5], v205 offset:6928
	v_lshlrev_b32_e32 v11, 16, v67
	v_lshlrev_b32_e32 v10, 16, v66
	s_waitcnt lgkmcnt(0)
	v_mov_b32_e32 v12, v6
	v_mov_b32_e32 v13, v8
	v_pk_mul_f32 v[10:11], v[12:13], v[10:11]
	v_and_b32_e32 v13, 0xffff0000, v67
	v_and_b32_e32 v12, 0xffff0000, v66
	v_mov_b32_e32 v8, v7
	v_pk_mul_f32 v[6:7], v[8:9], v[12:13]
	v_lshlrev_b32_e32 v9, 16, v69
	v_lshlrev_b32_e32 v8, 16, v68
	v_mov_b32_e32 v12, v2
	v_mov_b32_e32 v13, v4
	v_pk_mul_f32 v[8:9], v[12:13], v[8:9]
	v_and_b32_e32 v13, 0xffff0000, v69
	v_and_b32_e32 v12, 0xffff0000, v68
	v_mov_b32_e32 v4, v3
	v_pk_mul_f32 v[2:3], v[4:5], v[12:13]
	v_bfe_u32 v12, v7, 16, 1
	v_bfe_u32 v4, v3, 16, 1
	v_bfe_u32 v5, v2, 16, 1
	v_bfe_u32 v13, v6, 16, 1
	v_add3_u32 v7, v7, v12, s53
	v_add3_u32 v3, v3, v4, s53
	v_bfe_u32 v4, v10, 16, 1
	v_bfe_u32 v12, v8, 16, 1
	v_add3_u32 v6, v6, v13, s53
	v_add3_u32 v2, v2, v5, s53
	v_bfe_u32 v5, v11, 16, 1
	v_bfe_u32 v13, v9, 16, 1
	v_add3_u32 v8, v8, v12, s53
	v_add3_u32 v4, v10, v4, s53
	v_add3_u32 v9, v9, v13, s53
	v_add3_u32 v5, v11, v5, s53
	v_lshrrev_b32_e32 v10, 16, v4
	v_lshrrev_b32_e32 v4, 16, v8
	v_lshrrev_b32_e32 v11, 16, v5
	v_lshrrev_b32_e32 v5, 16, v9
	v_and_or_b32 v4, v2, s77, v4
	v_and_or_b32 v2, v6, s77, v10
	v_add_co_u32_e32 v6, vcc, s0, v114
	v_and_or_b32 v5, v3, s77, v5
	v_and_or_b32 v3, v7, s77, v11
	v_addc_co_u32_e32 v7, vcc, 0, v115, vcc
	global_store_dwordx4 v[6:7], v[2:5], off
	s_waitcnt lgkmcnt(0)
	ds_read_b128 v[2:5], v249 offset:17408
	ds_read_b128 v[66:69], v249 offset:17440
	s_waitcnt lgkmcnt(0)
	v_mfma_f32_32x32x16_bf16 v[2:17], v[2:5], v[82:85], 0
	s_mov_b32 s0, 0x80000
	v_mfma_f32_32x32x16_bf16 v[2:17], v[66:69], v[86:89], v[2:17]
	ds_read_b128 v[66:69], v249 offset:17472
	s_waitcnt lgkmcnt(0)
	v_mfma_f32_32x32x16_bf16 v[2:17], v[66:69], v[90:93], v[2:17]
	ds_read_b128 v[66:69], v249 offset:17504
	s_waitcnt lgkmcnt(0)
	v_mfma_f32_32x32x16_bf16 v[2:17], v[66:69], v[94:97], v[2:17]
	ds_read_b128 v[66:69], v249 offset:17536
	s_waitcnt lgkmcnt(0)
	v_mfma_f32_32x32x16_bf16 v[2:17], v[66:69], v[98:101], v[2:17]
	ds_read_b128 v[66:69], v249 offset:17568
	s_waitcnt lgkmcnt(0)
	v_mfma_f32_32x32x16_bf16 v[2:17], v[66:69], v[102:105], v[2:17]
	ds_read_b128 v[66:69], v249 offset:17600
	s_waitcnt lgkmcnt(0)
	v_mfma_f32_32x32x16_bf16 v[2:17], v[66:69], v[106:109], v[2:17]
	ds_read_b128 v[66:69], v249 offset:17632
	ds_read_b32 v70, v189
	s_waitcnt lgkmcnt(0)
	v_mfma_f32_32x32x16_bf16 v[2:17], v[66:69], v[110:113], v[2:17]
	s_nop 11
	v_add_f32_e32 v2, v2, v70
	ds_write_b32 v250, v2
	ds_read_b32 v2, v190
	s_waitcnt lgkmcnt(0)
	v_add_f32_e32 v2, v3, v2
	ds_write_b32 v204, v2
	ds_read_b32 v2, v191
	s_waitcnt lgkmcnt(0)
	v_add_f32_e32 v2, v4, v2
	ds_write_b32 v204, v2 offset:144
	ds_read_b32 v2, v192
	s_waitcnt lgkmcnt(0)
	v_add_f32_e32 v2, v5, v2
	ds_write_b32 v204, v2 offset:288
	ds_read_b32 v2, v193
	s_waitcnt lgkmcnt(0)
	v_add_f32_e32 v2, v6, v2
	ds_write_b32 v204, v2 offset:1008
	ds_read_b32 v2, v194
	s_waitcnt lgkmcnt(0)
	v_add_f32_e32 v2, v7, v2
	ds_write_b32 v204, v2 offset:1152
	ds_read_b32 v2, v195
	s_waitcnt lgkmcnt(0)
	v_add_f32_e32 v2, v8, v2
	ds_write_b32 v204, v2 offset:1296
	ds_read_b32 v2, v196
	s_waitcnt lgkmcnt(0)
	v_add_f32_e32 v2, v9, v2
	ds_write_b32 v204, v2 offset:1440
	ds_read_b32 v2, v197
	s_waitcnt lgkmcnt(0)
	v_add_f32_e32 v2, v10, v2
	ds_write_b32 v204, v2 offset:2160
	ds_read_b32 v2, v198
	s_waitcnt lgkmcnt(0)
	v_add_f32_e32 v2, v11, v2
	ds_write_b32 v204, v2 offset:2304
	ds_read_b32 v2, v199
	s_waitcnt lgkmcnt(0)
	v_add_f32_e32 v2, v12, v2
	ds_write_b32 v204, v2 offset:2448
	ds_read_b32 v2, v200
	s_waitcnt lgkmcnt(0)
	v_add_f32_e32 v2, v13, v2
	ds_write_b32 v204, v2 offset:2592
	ds_read_b32 v2, v201
	s_waitcnt lgkmcnt(0)
	v_add_f32_e32 v2, v14, v2
	ds_write_b32 v204, v2 offset:3312
	ds_read_b32 v2, v208
	s_waitcnt lgkmcnt(0)
	v_add_f32_e32 v2, v15, v2
	ds_write_b32 v204, v2 offset:3456
	ds_read_b32 v2, v209
	s_waitcnt lgkmcnt(0)
	v_add_f32_e32 v2, v16, v2
	ds_write_b32 v204, v2 offset:3600
	ds_read_b32 v2, v210
	s_waitcnt lgkmcnt(0)
	v_add_f32_e32 v2, v17, v2
	ds_write_b32 v204, v2 offset:3744
	ds_read_b128 v[2:5], v249 offset:26112
	ds_read_b128 v[66:69], v249 offset:26144
	s_waitcnt lgkmcnt(0)
	v_mfma_f32_32x32x16_bf16 v[2:17], v[2:5], v[82:85], 0
	v_mfma_f32_32x32x16_bf16 v[2:17], v[66:69], v[86:89], v[2:17]
	ds_read_b128 v[66:69], v249 offset:26176
	s_waitcnt lgkmcnt(0)
	v_mfma_f32_32x32x16_bf16 v[2:17], v[66:69], v[90:93], v[2:17]
	ds_read_b128 v[66:69], v249 offset:26208
	s_waitcnt lgkmcnt(0)
	v_mfma_f32_32x32x16_bf16 v[2:17], v[66:69], v[94:97], v[2:17]
	ds_read_b128 v[66:69], v249 offset:26240
	s_waitcnt lgkmcnt(0)
	v_mfma_f32_32x32x16_bf16 v[2:17], v[66:69], v[98:101], v[2:17]
	ds_read_b128 v[66:69], v249 offset:26272
	s_waitcnt lgkmcnt(0)
	v_mfma_f32_32x32x16_bf16 v[2:17], v[66:69], v[102:105], v[2:17]
	ds_read_b128 v[66:69], v249 offset:26304
	s_waitcnt lgkmcnt(0)
	v_mfma_f32_32x32x16_bf16 v[2:17], v[66:69], v[106:109], v[2:17]
	ds_read_b128 v[66:69], v249 offset:26336
	ds_read_b32 v70, v211
	s_waitcnt lgkmcnt(0)
	v_mfma_f32_32x32x16_bf16 v[2:17], v[66:69], v[110:113], v[2:17]
	s_nop 11
	v_add_f32_e32 v2, v2, v70
	ds_write_b32 v204, v2 offset:4464
	ds_read_b32 v2, v212
	s_waitcnt lgkmcnt(0)
	v_add_f32_e32 v2, v3, v2
	ds_write_b32 v204, v2 offset:4608
	ds_read_b32 v2, v213
	s_waitcnt lgkmcnt(0)
	v_add_f32_e32 v2, v4, v2
	ds_write_b32 v204, v2 offset:4752
	ds_read_b32 v2, v214
	s_waitcnt lgkmcnt(0)
	v_add_f32_e32 v2, v5, v2
	ds_write_b32 v204, v2 offset:4896
	ds_read_b32 v2, v215
	s_waitcnt lgkmcnt(0)
	v_add_f32_e32 v2, v6, v2
	ds_write_b32 v204, v2 offset:5616
	ds_read_b32 v2, v216
	s_waitcnt lgkmcnt(0)
	v_add_f32_e32 v2, v7, v2
	ds_write_b32 v204, v2 offset:5760
	ds_read_b32 v2, v217
	s_waitcnt lgkmcnt(0)
	v_add_f32_e32 v2, v8, v2
	ds_write_b32 v204, v2 offset:5904
	ds_read_b32 v2, v218
	s_waitcnt lgkmcnt(0)
	v_add_f32_e32 v2, v9, v2
	ds_write_b32 v204, v2 offset:6048
	ds_read_b32 v2, v219
	s_waitcnt lgkmcnt(0)
	v_add_f32_e32 v2, v10, v2
	ds_write_b32 v204, v2 offset:6768
	ds_read_b32 v2, v220
	v_lshlrev_b32_e32 v10, 16, v62
	s_waitcnt lgkmcnt(0)
	v_add_f32_e32 v2, v11, v2
	ds_write_b32 v204, v2 offset:6912
	ds_read_b32 v2, v221
	v_lshlrev_b32_e32 v11, 16, v63
	s_waitcnt lgkmcnt(0)
	v_add_f32_e32 v2, v12, v2
	ds_write_b32 v204, v2 offset:7056
	ds_read_b32 v2, v222
	s_waitcnt lgkmcnt(0)
	v_add_f32_e32 v2, v13, v2
	ds_write_b32 v204, v2 offset:7200
	ds_read_b32 v2, v223
	s_waitcnt lgkmcnt(0)
	v_add_f32_e32 v2, v14, v2
	ds_write_b32 v204, v2 offset:7920
	ds_read_b32 v2, v224
	s_waitcnt lgkmcnt(0)
	v_add_f32_e32 v2, v15, v2
	ds_write_b32 v204, v2 offset:8064
	ds_read_b32 v2, v225
	s_waitcnt lgkmcnt(0)
	v_add_f32_e32 v2, v16, v2
	ds_write_b32 v204, v2 offset:8208
	ds_read_b32 v2, v226
	s_waitcnt lgkmcnt(0)
	v_add_f32_e32 v2, v17, v2
	ds_write_b32 v204, v2 offset:8352
	s_waitcnt lgkmcnt(0)
	ds_read_b128 v[2:5], v205
	ds_read_b128 v[6:9], v205 offset:16
	s_waitcnt lgkmcnt(0)
	v_mov_b32_e32 v12, v2
	v_mov_b32_e32 v13, v4
	v_pk_mul_f32 v[10:11], v[12:13], v[10:11]
	v_and_b32_e32 v13, 0xffff0000, v63
	v_and_b32_e32 v12, 0xffff0000, v62
	v_mov_b32_e32 v4, v3
	v_pk_mul_f32 v[2:3], v[4:5], v[12:13]
	v_lshlrev_b32_e32 v5, 16, v65
	v_lshlrev_b32_e32 v4, 16, v64
	v_mov_b32_e32 v12, v6
	v_mov_b32_e32 v13, v8
	v_pk_mul_f32 v[4:5], v[12:13], v[4:5]
	v_and_b32_e32 v13, 0xffff0000, v65
	v_and_b32_e32 v12, 0xffff0000, v64
	v_mov_b32_e32 v8, v7
	v_pk_mul_f32 v[6:7], v[8:9], v[12:13]
	v_bfe_u32 v12, v3, 16, 1
	v_bfe_u32 v8, v7, 16, 1
	v_bfe_u32 v9, v6, 16, 1
	v_bfe_u32 v13, v2, 16, 1
	v_add3_u32 v2, v2, v13, s53
	v_add3_u32 v3, v3, v12, s53
	v_add3_u32 v6, v6, v9, s53
	v_add3_u32 v7, v7, v8, s53
	v_bfe_u32 v8, v10, 16, 1
	v_bfe_u32 v9, v11, 16, 1
	v_bfe_u32 v12, v4, 16, 1
	v_bfe_u32 v13, v5, 16, 1
	v_add3_u32 v5, v5, v13, s53
	v_add3_u32 v4, v4, v12, s53
	v_add3_u32 v9, v11, v9, s53
	v_add3_u32 v8, v10, v8, s53
	v_lshrrev_b32_e32 v8, 16, v8
	v_lshrrev_b32_e32 v9, 16, v9
	v_lshrrev_b32_e32 v4, 16, v4
	v_lshrrev_b32_e32 v5, 16, v5
	v_and_or_b32 v5, v7, s77, v5
	v_and_or_b32 v4, v6, s77, v4
	v_and_or_b32 v3, v3, s77, v9
	v_and_or_b32 v2, v2, s77, v8
	v_add_co_u32_e32 v10, vcc, s0, v114
	ds_read_b128 v[6:9], v205 offset:2304
	s_nop 0
	v_addc_co_u32_e32 v11, vcc, 0, v115, vcc
	global_store_dwordx4 v[10:11], v[2:5], off
	ds_read_b128 v[2:5], v205 offset:2320
	v_lshlrev_b32_e32 v11, 16, v59
	v_lshlrev_b32_e32 v10, 16, v58
	s_waitcnt lgkmcnt(0)
	v_mov_b32_e32 v12, v6
	v_mov_b32_e32 v13, v8
	v_pk_mul_f32 v[10:11], v[12:13], v[10:11]
	v_and_b32_e32 v13, 0xffff0000, v59
	v_and_b32_e32 v12, 0xffff0000, v58
	v_mov_b32_e32 v8, v7
	v_pk_mul_f32 v[6:7], v[8:9], v[12:13]
	v_lshlrev_b32_e32 v9, 16, v61
	v_lshlrev_b32_e32 v8, 16, v60
	v_mov_b32_e32 v12, v2
	v_mov_b32_e32 v13, v4
	v_pk_mul_f32 v[8:9], v[12:13], v[8:9]
	v_and_b32_e32 v13, 0xffff0000, v61
	v_and_b32_e32 v12, 0xffff0000, v60
	v_mov_b32_e32 v4, v3
	v_pk_mul_f32 v[2:3], v[4:5], v[12:13]
	v_bfe_u32 v12, v7, 16, 1
	v_bfe_u32 v4, v3, 16, 1
	v_bfe_u32 v5, v2, 16, 1
	v_bfe_u32 v13, v6, 16, 1
	v_add3_u32 v6, v6, v13, s53
	v_add3_u32 v7, v7, v12, s53
	v_add3_u32 v2, v2, v5, s53
	v_add3_u32 v3, v3, v4, s53
	v_bfe_u32 v4, v10, 16, 1
	v_bfe_u32 v5, v11, 16, 1
	v_bfe_u32 v12, v8, 16, 1
	v_bfe_u32 v13, v9, 16, 1
	v_add3_u32 v9, v9, v13, s53
	v_add3_u32 v8, v8, v12, s53
	v_add3_u32 v5, v11, v5, s53
	v_add3_u32 v4, v10, v4, s53
	v_lshrrev_b32_e32 v10, 16, v4
	v_lshrrev_b32_e32 v11, 16, v5
	v_lshrrev_b32_e32 v4, 16, v8
	v_lshrrev_b32_e32 v5, 16, v9
	s_mov_b32 s0, 0xa0000
	v_and_or_b32 v5, v3, s77, v5
	v_and_or_b32 v4, v2, s77, v4
	v_and_or_b32 v3, v7, s77, v11
	v_and_or_b32 v2, v6, s77, v10
	v_add_co_u32_e32 v10, vcc, s0, v114
	ds_read_b128 v[6:9], v205 offset:4608
	s_nop 0
	v_addc_co_u32_e32 v11, vcc, 0, v115, vcc
	global_store_dwordx4 v[10:11], v[2:5], off
	ds_read_b128 v[2:5], v205 offset:4624
	v_lshlrev_b32_e32 v11, 16, v55
	v_lshlrev_b32_e32 v10, 16, v54
	s_waitcnt lgkmcnt(0)
	v_mov_b32_e32 v12, v6
	v_mov_b32_e32 v13, v8
	v_pk_mul_f32 v[10:11], v[12:13], v[10:11]
	v_and_b32_e32 v13, 0xffff0000, v55
	v_and_b32_e32 v12, 0xffff0000, v54
	v_mov_b32_e32 v8, v7
	v_pk_mul_f32 v[6:7], v[8:9], v[12:13]
	v_lshlrev_b32_e32 v9, 16, v57
	v_lshlrev_b32_e32 v8, 16, v56
	v_mov_b32_e32 v12, v2
	v_mov_b32_e32 v13, v4
	v_pk_mul_f32 v[8:9], v[12:13], v[8:9]
	v_and_b32_e32 v13, 0xffff0000, v57
	v_and_b32_e32 v12, 0xffff0000, v56
	v_mov_b32_e32 v4, v3
	v_pk_mul_f32 v[2:3], v[4:5], v[12:13]
	v_bfe_u32 v12, v7, 16, 1
	v_bfe_u32 v4, v3, 16, 1
	v_bfe_u32 v5, v2, 16, 1
	v_bfe_u32 v13, v6, 16, 1
	v_add3_u32 v6, v6, v13, s53
	v_add3_u32 v7, v7, v12, s53
	v_add3_u32 v2, v2, v5, s53
	v_add3_u32 v3, v3, v4, s53
	v_bfe_u32 v4, v10, 16, 1
	v_bfe_u32 v5, v11, 16, 1
	v_bfe_u32 v12, v8, 16, 1
	v_bfe_u32 v13, v9, 16, 1
	v_add3_u32 v9, v9, v13, s53
	v_add3_u32 v8, v8, v12, s53
	v_add3_u32 v5, v11, v5, s53
	v_add3_u32 v4, v10, v4, s53
	v_lshrrev_b32_e32 v10, 16, v4
	v_lshrrev_b32_e32 v11, 16, v5
	v_lshrrev_b32_e32 v4, 16, v8
	v_lshrrev_b32_e32 v5, 16, v9
	s_mov_b32 s0, 0xc0000
	v_and_or_b32 v5, v3, s77, v5
	v_and_or_b32 v4, v2, s77, v4
	v_and_or_b32 v3, v7, s77, v11
	v_and_or_b32 v2, v6, s77, v10
	v_add_co_u32_e32 v10, vcc, s0, v114
	ds_read_b128 v[6:9], v205 offset:6912
	s_nop 0
	v_addc_co_u32_e32 v11, vcc, 0, v115, vcc
	global_store_dwordx4 v[10:11], v[2:5], off
	ds_read_b128 v[2:5], v205 offset:6928
	v_lshlrev_b32_e32 v11, 16, v51
	v_lshlrev_b32_e32 v10, 16, v50
	s_waitcnt lgkmcnt(0)
	v_mov_b32_e32 v12, v6
	v_mov_b32_e32 v13, v8
	v_pk_mul_f32 v[10:11], v[12:13], v[10:11]
	v_and_b32_e32 v13, 0xffff0000, v51
	v_and_b32_e32 v12, 0xffff0000, v50
	v_mov_b32_e32 v8, v7
	v_pk_mul_f32 v[6:7], v[8:9], v[12:13]
	v_lshlrev_b32_e32 v9, 16, v53
	v_lshlrev_b32_e32 v8, 16, v52
	v_mov_b32_e32 v12, v2
	v_mov_b32_e32 v13, v4
	v_pk_mul_f32 v[8:9], v[12:13], v[8:9]
	v_and_b32_e32 v13, 0xffff0000, v53
	v_and_b32_e32 v12, 0xffff0000, v52
	v_mov_b32_e32 v4, v3
	v_pk_mul_f32 v[2:3], v[4:5], v[12:13]
	v_bfe_u32 v12, v7, 16, 1
	v_bfe_u32 v4, v3, 16, 1
	v_bfe_u32 v5, v2, 16, 1
	v_bfe_u32 v13, v6, 16, 1
	v_add3_u32 v7, v7, v12, s53
	v_add3_u32 v3, v3, v4, s53
	v_bfe_u32 v4, v10, 16, 1
	v_bfe_u32 v12, v8, 16, 1
	v_add3_u32 v6, v6, v13, s53
	v_add3_u32 v2, v2, v5, s53
	v_bfe_u32 v5, v11, 16, 1
	v_bfe_u32 v13, v9, 16, 1
	v_add3_u32 v8, v8, v12, s53
	v_add3_u32 v4, v10, v4, s53
	v_add3_u32 v9, v9, v13, s53
	v_add3_u32 v5, v11, v5, s53
	v_lshrrev_b32_e32 v10, 16, v4
	v_lshrrev_b32_e32 v4, 16, v8
	s_mov_b32 s0, 0xe0000
	v_lshrrev_b32_e32 v11, 16, v5
	v_lshrrev_b32_e32 v5, 16, v9
	v_and_or_b32 v4, v2, s77, v4
	v_and_or_b32 v2, v6, s77, v10
	v_add_co_u32_e32 v6, vcc, s0, v114
	s_add_u32 s0, s78, s8
	v_and_or_b32 v5, v3, s77, v5
	v_and_or_b32 v3, v7, s77, v11
	v_addc_co_u32_e32 v7, vcc, 0, v115, vcc
	s_addc_u32 s1, s79, s9
	global_store_dwordx4 v[6:7], v[2:5], off
	s_add_u32 s0, s0, s10
	s_waitcnt lgkmcnt(0)
	s_addc_u32 s1, s1, s11
	s_add_u32 s8, s0, 0x20000
	s_nop 4
	global_load_dwordx4 v[78:81], v130, s[0:1]
	s_addc_u32 s9, s1, 0
	s_nop 4
	global_load_dwordx4 v[74:77], v130, s[8:9]
	s_add_u32 s8, s0, 0x40000
	s_addc_u32 s9, s1, 0
	s_nop 4
	global_load_dwordx4 v[70:73], v130, s[8:9]
	s_add_u32 s8, s0, 0x60000
	s_addc_u32 s9, s1, 0
	s_nop 4
	global_load_dwordx4 v[66:69], v130, s[8:9]
	s_add_u32 s8, s0, 0x80000
	s_addc_u32 s9, s1, 0
	s_nop 4
	global_load_dwordx4 v[62:65], v130, s[8:9]
	s_add_u32 s8, s0, 0xa0000
	s_addc_u32 s9, s1, 0
	s_nop 4
	global_load_dwordx4 v[58:61], v130, s[8:9]
	s_add_u32 s8, s0, 0xc0000
	s_addc_u32 s9, s1, 0
	s_nop 4
	global_load_dwordx4 v[54:57], v130, s[8:9]
	s_add_u32 s0, s0, 0xe0000
	s_addc_u32 s1, s1, 0
	s_nop 4
	global_load_dwordx4 v[50:53], v130, s[0:1]
	s_sub_i32 s17, s17, s14
	s_sub_i32 s16, s16, s15
	s_and_b64 vcc, exec, s[6:7]
	s_barrier
	s_cbranch_vccz .LBB0_634
	s_mov_b32 s10, s19
	s_branch .LBB0_625
